# wave_sum butterflies in retpost, LN1, LN2: ds_bpermute replaced by permlane32/16_swap + DPP row_ror/quad_perm with identical pairing (bit-identical sums)
# speedup vs baseline: 1.0131x; 1.0015x over previous
; __device__ __forceinline__ float wave_sum(float v) {
; #pragma unroll
;   for (int o = 32; o >= 1; o >>= 1) v += __shfl_xor(v, o);
;   return v;
; }
; __device__ __forceinline__ void ln_finish_row(int r, int lane, f32x4 (&x)[8], float* dstf, bf16_t* dstb, const float* g, const float* bta) {
;   float sm = 0.f;
; #pragma unroll
;   for (int k = 0; k < 8; ++k) sm += x[k][0] + x[k][1] + x[k][2] + x[k][3];
;   const float mean = wave_sum(sm) * (1.0f / 2048.0f);
;   float q = 0.f;
; #pragma unroll
;   for (int k = 0; k < 8; ++k) { x[k] = x[k] - mean; q += x[k][0] * x[k][0] + x[k][1] * x[k][1] + x[k][2] * x[k][2] + x[k][3] * x[k][3]; }
;   const float rstd = rsqrtf(wave_sum(q) * (1.0f / 2048.0f) + LN_EPS);
.LBB0_158:
	s_or_b64 exec, exec, s[48:49]
	s_waitcnt vmcnt(0)
	v_add_f32_e32 v67, v24, v25
	v_add_f32_e32 v67, v26, v67
	v_add_f32_e32 v103, v32, v33
	v_add_f32_e32 v67, v27, v67
	v_add_f32_e32 v103, v34, v103
	v_add_f32_e32 v67, 0, v67
	v_add_f32_e32 v103, v35, v103
	v_add_f32_e32 v67, v67, v103
	v_add_f32_e32 v103, v36, v37
	v_add_f32_e32 v103, v38, v103
	v_add_f32_e32 v103, v39, v103
	v_add_f32_e32 v67, v67, v103
	v_add_f32_e32 v103, v44, v45
	v_mov_b32_e32 v116, v48
	v_mov_b32_e32 v117, v52
	v_mov_b32_e32 v118, v49
	v_mov_b32_e32 v119, v53
	v_add_f32_e32 v103, v46, v103
	v_pk_add_f32 v[116:117], v[116:117], v[118:119]
	v_mov_b32_e32 v118, v50
	v_mov_b32_e32 v119, v54
	v_add_f32_e32 v103, v47, v103
	v_pk_add_f32 v[116:117], v[118:119], v[116:117]
	v_mov_b32_e32 v118, v51
	v_mov_b32_e32 v119, v55
	v_add_f32_e32 v67, v67, v103
	v_pk_add_f32 v[116:117], v[118:119], v[116:117]
	v_mov_b32_e32 v118, v57
	v_add_f32_e32 v67, v67, v116
	v_add_f32_e32 v67, v67, v117
	v_mov_b32_e32 v116, v56
	v_mov_b32_e32 v117, v60
	v_mov_b32_e32 v119, v61
	v_pk_add_f32 v[116:117], v[116:117], v[118:119]
	v_mov_b32_e32 v118, v58
	v_mov_b32_e32 v119, v62
	v_pk_add_f32 v[116:117], v[118:119], v[116:117]
	v_mov_b32_e32 v118, v59
	v_mov_b32_e32 v119, v63
	v_pk_add_f32 v[116:117], v[118:119], v[116:117]
	global_load_dwordx4 v[130:133], v[72:73], off
	global_load_dwordx4 v[134:137], v[74:75], off
	v_add_f32_e32 v67, v67, v116
	v_add_f32_e32 v67, v67, v117
	v_mov_b32_e32 v103, v67
	s_nop 1
	v_permlane32_swap_b32_e32 v103, v67
	s_mov_b32 s29, 0x800000
	s_waitcnt lgkmcnt(0)
	v_add_f32_e32 v67, v67, v103
	v_mov_b32_e32 v103, v67
	s_nop 1
	v_permlane16_swap_b32_e32 v103, v67
	s_waitcnt lgkmcnt(0)
	v_add_f32_e32 v67, v67, v103
	s_nop 1
	v_mov_b32_dpp v103, v67 row_ror:8 row_mask:0xf bank_mask:0xf
	s_waitcnt lgkmcnt(0)
	v_add_f32_e32 v67, v67, v103
	s_nop 1
	v_mov_b32_dpp v103, v67 row_ror:4 row_mask:0xf bank_mask:0xf
	s_waitcnt lgkmcnt(0)
	v_add_f32_e32 v67, v67, v103
	s_nop 1
	v_mov_b32_dpp v103, v67 quad_perm:[2,3,0,1] row_mask:0xf bank_mask:0xf
	s_waitcnt lgkmcnt(0)
	v_add_f32_e32 v67, v67, v103
	s_nop 1
	v_mov_b32_dpp v103, v67 quad_perm:[1,0,3,2] row_mask:0xf bank_mask:0xf
	s_waitcnt lgkmcnt(0)
	v_add_f32_e32 v67, v67, v103
	v_fmac_f32_e32 v25, 0xba000000, v67
	v_fmac_f32_e32 v33, 0xba000000, v67
	v_fmamk_f32 v123, v67, 0xba000000, v27
	v_fmamk_f32 v122, v67, 0xba000000, v26
	v_fmamk_f32 v24, v67, 0xba000000, v24
	v_mul_f32_e32 v26, v25, v25
	v_fmamk_f32 v32, v67, 0xba000000, v32
	v_mul_f32_e32 v27, v33, v33
	v_fmac_f32_e32 v26, v24, v24
	v_fmamk_f32 v120, v67, 0xba000000, v34
	v_fmac_f32_e32 v27, v32, v32
	v_fmac_f32_e32 v26, v122, v122
	v_fmamk_f32 v121, v67, 0xba000000, v35
	v_fmac_f32_e32 v27, v120, v120
	v_fmac_f32_e32 v26, v123, v123
	v_fmac_f32_e32 v27, v121, v121
	v_fmac_f32_e32 v37, 0xba000000, v67
	v_add_f32_e32 v26, v26, v27
	v_fmamk_f32 v36, v67, 0xba000000, v36
	v_mul_f32_e32 v27, v37, v37
	v_fmamk_f32 v118, v67, 0xba000000, v38
	v_fmac_f32_e32 v27, v36, v36
	v_fmamk_f32 v119, v67, 0xba000000, v39
	v_fmac_f32_e32 v27, v118, v118
	v_fmac_f32_e32 v27, v119, v119
	v_fmac_f32_e32 v45, 0xba000000, v67
	v_add_f32_e32 v26, v27, v26
	v_fmamk_f32 v44, v67, 0xba000000, v44
	v_mul_f32_e32 v27, v45, v45
	v_fmamk_f32 v116, v67, 0xba000000, v46
	v_fmac_f32_e32 v27, v44, v44
	v_fmamk_f32 v117, v67, 0xba000000, v47
	v_fmac_f32_e32 v27, v116, v116
	v_fmamk_f32 v49, v67, 0xba000000, v49
	v_fmamk_f32 v53, v67, 0xba000000, v53
	v_fmac_f32_e32 v27, v117, v117
	v_fmac_f32_e32 v48, 0xba000000, v67
	v_fmac_f32_e32 v52, 0xba000000, v67
	v_mov_b32_e32 v38, v53
	v_mov_b32_e32 v39, v49
	v_add_f32_e32 v46, v27, v26
	v_fmamk_f32 v50, v67, 0xba000000, v50
	v_fmamk_f32 v34, v67, 0xba000000, v54
	v_mov_b32_e32 v26, v52
	v_mov_b32_e32 v27, v48
	v_pk_mul_f32 v[38:39], v[38:39], v[38:39]
	v_fmamk_f32 v51, v67, 0xba000000, v51
	v_fmamk_f32 v35, v67, 0xba000000, v55
	v_pk_fma_f32 v[26:27], v[26:27], v[26:27], v[38:39]
	v_mov_b32_e32 v38, v34
	v_mov_b32_e32 v39, v50
	v_pk_fma_f32 v[26:27], v[38:39], v[38:39], v[26:27]
	v_mov_b32_e32 v38, v35
	v_mov_b32_e32 v39, v51
	v_pk_fma_f32 v[26:27], v[38:39], v[38:39], v[26:27]
	v_fmamk_f32 v57, v67, 0xba000000, v57
	v_fmamk_f32 v61, v67, 0xba000000, v61
	v_add_f32_e32 v27, v27, v46
	v_fmac_f32_e32 v56, 0xba000000, v67
	v_fmac_f32_e32 v60, 0xba000000, v67
	v_mov_b32_e32 v54, v61
	v_mov_b32_e32 v55, v57
	v_add_f32_e32 v103, v26, v27
	v_fmamk_f32 v38, v67, 0xba000000, v58
	v_fmamk_f32 v26, v67, 0xba000000, v62
	v_mov_b32_e32 v46, v60
	v_mov_b32_e32 v47, v56
	v_pk_mul_f32 v[54:55], v[54:55], v[54:55]
	v_fmamk_f32 v39, v67, 0xba000000, v59
	v_fmamk_f32 v27, v67, 0xba000000, v63
	v_pk_fma_f32 v[46:47], v[46:47], v[46:47], v[54:55]
	v_mov_b32_e32 v54, v26
	v_mov_b32_e32 v55, v38
	v_pk_fma_f32 v[46:47], v[54:55], v[54:55], v[46:47]
	v_mov_b32_e32 v54, v27
	v_mov_b32_e32 v55, v39
	v_pk_fma_f32 v[46:47], v[54:55], v[54:55], v[46:47]
	s_nop 0
	v_add_f32_e32 v47, v47, v103
	v_add_f32_e32 v46, v46, v47
	v_mov_b32_e32 v47, v46
	s_nop 1
	v_permlane32_swap_b32_e32 v47, v46
	s_waitcnt lgkmcnt(0)
	v_add_f32_e32 v46, v46, v47
	v_mov_b32_e32 v47, v46
	s_nop 1
	v_permlane16_swap_b32_e32 v47, v46
	s_waitcnt lgkmcnt(0)
	v_add_f32_e32 v46, v46, v47
	s_nop 1
	v_mov_b32_dpp v47, v46 row_ror:8 row_mask:0xf bank_mask:0xf
	s_waitcnt lgkmcnt(0)
	v_add_f32_e32 v46, v46, v47
	s_nop 1
	v_mov_b32_dpp v47, v46 row_ror:4 row_mask:0xf bank_mask:0xf
	s_waitcnt lgkmcnt(0)
	v_add_f32_e32 v46, v46, v47
	s_nop 1
	v_mov_b32_dpp v47, v46 quad_perm:[2,3,0,1] row_mask:0xf bank_mask:0xf
	s_waitcnt lgkmcnt(0)
	v_add_f32_e32 v46, v46, v47
	s_nop 1
	v_mov_b32_dpp v47, v46 quad_perm:[1,0,3,2] row_mask:0xf bank_mask:0xf
	s_waitcnt lgkmcnt(0)
; __device__ __forceinline__ u32x2 pack4(f32x4 v) { u32x2 r; r[0] = cvt_pk(v[0], v[1]); r[1] = cvt_pk(v[2], v[3]); return r; }
; __device__ __forceinline__ void ln_finish_row(int r, int lane, f32x4 (&x)[8], float* dstf, bf16_t* dstb, const float* g, const float* bta) {
;     ...
;   const float rstd = rsqrtf(wave_sum(q) * (1.0f / 2048.0f) + LN_EPS);
; #pragma unroll
;   for (int k = 0; k < 8; ++k) {
;     const int col = 256 * k + 4 * lane;
;     const f32x4 gg = *(const f32x4*)(g + col), bb = *(const f32x4*)(bta + col);
;     const f32x4 y = x[k] * rstd * gg + bb;
;     *(f32x4*)(dstf + (size_t)r * 2048 + col) = y;
;     if (dstb) *(u32x2*)(dstb + (size_t)r * 2048 + col) = pack4(y);
;   }
	v_add_f32_e32 v46, v46, v47
	v_fmamk_f32 v46, v46, 0x3a000000, v228
	v_cmp_gt_f32_e32 vcc, s29, v46
	v_mul_f32_e32 v47, 0x4b800000, v46
	s_mov_b32 s29, 0x19f09000
	v_cndmask_b32_e32 v46, v46, v47, vcc
	v_rsq_f32_e32 v46, v46
	s_nop 0
	v_mul_f32_e32 v47, 0x45800000, v46
	v_cndmask_b32_e32 v46, v46, v47, vcc
	v_pk_mul_f32 v[54:55], v[122:123], v[46:47] op_sel_hi:[1,0]
	v_pk_mul_f32 v[24:25], v[24:25], v[46:47] op_sel_hi:[1,0]
	s_waitcnt vmcnt(0)
	v_pk_fma_f32 v[132:133], v[132:133], v[54:55], v[136:137]
	v_lshl_add_u64 v[54:55], s[24:25], 0, v[96:97]
	v_pk_fma_f32 v[130:131], v[130:131], v[24:25], v[134:135]
	v_add_co_u32_e32 v54, vcc, s29, v54
	v_cvt_pk_bf16_f32 v24, v130, v131
	v_cvt_pk_bf16_f32 v25, v132, v133
	v_addc_co_u32_e32 v55, vcc, 0, v55, vcc
	global_store_dwordx4 v[112:113], v[130:133], off
	global_store_dwordx2 v[54:55], v[24:25], off
	global_load_dwordx4 v[130:133], v[72:73], off offset:1024
	s_nop 0
	global_load_dwordx4 v[134:137], v[74:75], off offset:1024
	v_pk_mul_f32 v[24:25], v[120:121], v[46:47] op_sel_hi:[1,0]
	v_pk_mul_f32 v[32:33], v[32:33], v[46:47] op_sel_hi:[1,0]
	s_mov_b32 s29, 0x109000
	v_pk_mul_f32 v[36:37], v[36:37], v[46:47] op_sel_hi:[1,0]
	v_pk_mul_f32 v[26:27], v[26:27], v[46:47] op_sel_hi:[1,0]
	s_waitcnt vmcnt(0)
	v_pk_fma_f32 v[120:121], v[130:131], v[32:33], v[134:135]
	v_pk_fma_f32 v[122:123], v[132:133], v[24:25], v[136:137]
	v_add_co_u32_e32 v24, vcc, s29, v110
	v_cvt_pk_bf16_f32 v32, v120, v121
	s_nop 0
	v_addc_co_u32_e32 v25, vcc, 0, v111, vcc
	v_cvt_pk_bf16_f32 v33, v122, v123
	global_store_dwordx4 v[24:25], v[120:123], off offset:1024
	global_store_dwordx2 v[54:55], v[32:33], off offset:512
	global_load_dwordx4 v[120:123], v[72:73], off offset:2048
	s_nop 0
	global_load_dwordx4 v[130:133], v[74:75], off offset:2048
	v_pk_mul_f32 v[32:33], v[118:119], v[46:47] op_sel_hi:[1,0]
	s_mov_b32 s29, 0x10a000
	s_waitcnt vmcnt(0)
	v_pk_fma_f32 v[118:119], v[120:121], v[36:37], v[130:131]
	v_pk_fma_f32 v[120:121], v[122:123], v[32:33], v[132:133]
	v_cvt_pk_bf16_f32 v32, v118, v119
	v_cvt_pk_bf16_f32 v33, v120, v121
	global_store_dwordx4 v[24:25], v[118:121], off offset:2048
	global_store_dwordx2 v[54:55], v[32:33], off offset:1024
	global_load_dwordx4 v[118:121], v[72:73], off offset:3072
	s_nop 0
	global_load_dwordx4 v[130:133], v[74:75], off offset:3072
	v_pk_mul_f32 v[32:33], v[116:117], v[46:47] op_sel_hi:[1,0]
	v_pk_mul_f32 v[36:37], v[44:45], v[46:47] op_sel_hi:[1,0]
	v_add_co_u32_e32 v44, vcc, s29, v110
	s_waitcnt vmcnt(0)
	v_pk_fma_f32 v[116:117], v[118:119], v[36:37], v[130:131]
	v_pk_fma_f32 v[118:119], v[120:121], v[32:33], v[132:133]
	global_store_dwordx4 v[24:25], v[116:119], off offset:3072
	v_cvt_pk_bf16_f32 v24, v116, v117
	v_cvt_pk_bf16_f32 v25, v118, v119
	global_store_dwordx2 v[54:55], v[24:25], off offset:1536
	global_load_dwordx4 v[116:119], v[76:77], off
	global_load_dwordx4 v[120:123], v[78:79], off
	v_pk_mul_f32 v[24:25], v[50:51], v[46:47] op_sel_hi:[1,0]
	v_pk_mul_f32 v[32:33], v[48:49], v[46:47] op_sel_hi:[1,0]
	v_addc_co_u32_e32 v45, vcc, 0, v111, vcc
	v_pk_mul_f32 v[36:37], v[56:57], v[46:47] op_sel_hi:[1,0]
	s_waitcnt vmcnt(0)
	v_pk_fma_f32 v[48:49], v[116:117], v[32:33], v[120:121]
	v_pk_fma_f32 v[50:51], v[118:119], v[24:25], v[122:123]
	v_cvt_pk_bf16_f32 v24, v48, v49
	v_cvt_pk_bf16_f32 v25, v50, v51
	global_store_dwordx4 v[44:45], v[48:51], off
	global_store_dwordx2 v[54:55], v[24:25], off offset:2048
	global_load_dwordx4 v[48:51], v[80:81], off
	s_nop 0
	global_load_dwordx4 v[110:113], v[82:83], off
	v_pk_mul_f32 v[24:25], v[34:35], v[46:47] op_sel_hi:[1,0]
	v_pk_mul_f32 v[32:33], v[52:53], v[46:47] op_sel_hi:[1,0]
	s_waitcnt vmcnt(0)
	v_pk_fma_f32 v[34:35], v[50:51], v[24:25], v[112:113]
	v_pk_fma_f32 v[32:33], v[48:49], v[32:33], v[110:111]
	v_cvt_pk_bf16_f32 v25, v34, v35
	v_cvt_pk_bf16_f32 v24, v32, v33
	global_store_dwordx4 v[44:45], v[32:35], off offset:1024
	global_store_dwordx2 v[54:55], v[24:25], off offset:2560
	global_load_dwordx4 v[32:35], v[84:85], off
	s_nop 0
	global_load_dwordx4 v[48:51], v[86:87], off
	v_pk_mul_f32 v[24:25], v[38:39], v[46:47] op_sel_hi:[1,0]
	s_waitcnt vmcnt(0)
	v_pk_fma_f32 v[32:33], v[32:33], v[36:37], v[48:49]
	v_pk_fma_f32 v[34:35], v[34:35], v[24:25], v[50:51]
	v_cvt_pk_bf16_f32 v24, v32, v33
	v_cvt_pk_bf16_f32 v25, v34, v35
	global_store_dwordx4 v[44:45], v[32:35], off offset:2048
	global_store_dwordx2 v[54:55], v[24:25], off offset:3072
	global_load_dwordx4 v[32:35], v[88:89], off
	s_nop 0
	global_load_dwordx4 v[36:39], v[90:91], off
	v_pk_mul_f32 v[24:25], v[60:61], v[46:47] op_sel_hi:[1,0]
	s_waitcnt vmcnt(0)
	v_pk_fma_f32 v[26:27], v[26:27], v[34:35], v[38:39]
	v_pk_fma_f32 v[24:25], v[24:25], v[32:33], v[36:37]
	global_store_dwordx4 v[44:45], v[24:27], off offset:3072
	s_nop 1
	v_cvt_pk_bf16_f32 v24, v24, v25
	v_cvt_pk_bf16_f32 v25, v26, v27
	global_store_dwordx2 v[54:55], v[24:25], off offset:3584
	s_and_saveexec_b64 s[38:39], s[36:37]
	s_cbranch_execz .LBB0_91
; __device__ __forceinline__ void ln_finish_row(int r, int lane, f32x4 (&x)[8], float* dstf, bf16_t* dstb, const float* g, const float* bta) {
;   float sm = 0.f;
; #pragma unroll
;   for (int k = 0; k < 8; ++k) sm += x[k][0] + x[k][1] + x[k][2] + x[k][3];
;   const float mean = wave_sum(sm) * (1.0f / 2048.0f);
;   float q = 0.f;
; #pragma unroll
;   for (int k = 0; k < 8; ++k) { x[k] = x[k] - mean; q += x[k][0] * x[k][0] + x[k][1] * x[k][1] + x[k][2] * x[k][2] + x[k][3] * x[k][3]; }
;   const float rstd = rsqrtf(wave_sum(q) * (1.0f / 2048.0f) + LN_EPS);
	v_add_f32_e32 v24, v0, v1
	v_add_f32_e32 v24, v2, v24
	v_add_f32_e32 v25, v4, v5
	v_add_f32_e32 v24, v3, v24
	v_add_f32_e32 v25, v6, v25
	v_add_f32_e32 v24, 0, v24
	v_add_f32_e32 v25, v7, v25
	v_add_f32_e32 v24, v25, v24
	v_add_f32_e32 v25, v8, v9
	v_add_f32_e32 v25, v10, v25
	v_add_f32_e32 v25, v11, v25
	v_add_f32_e32 v24, v25, v24
	v_add_f32_e32 v25, v12, v13
	v_add_f32_e32 v25, v14, v25
	v_add_f32_e32 v25, v15, v25
	v_add_f32_e32 v32, v25, v24
	v_mov_b32_e32 v24, v20
	v_mov_b32_e32 v25, v16
	v_mov_b32_e32 v26, v21
	v_mov_b32_e32 v27, v17
	v_pk_add_f32 v[24:25], v[24:25], v[26:27]
	v_mov_b32_e32 v26, v22
	v_mov_b32_e32 v27, v18
	v_pk_add_f32 v[24:25], v[26:27], v[24:25]
	v_mov_b32_e32 v26, v23
	v_mov_b32_e32 v27, v19
	v_pk_add_f32 v[24:25], v[26:27], v[24:25]
	v_mov_b32_e32 v26, v41
	v_add_f32_e32 v25, v25, v32
	v_add_f32_e32 v32, v24, v25
	v_mov_b32_e32 v24, v40
	v_mov_b32_e32 v25, v28
	v_mov_b32_e32 v27, v29
	v_pk_add_f32 v[24:25], v[24:25], v[26:27]
	v_mov_b32_e32 v26, v42
	v_mov_b32_e32 v27, v30
	v_pk_add_f32 v[24:25], v[26:27], v[24:25]
	v_mov_b32_e32 v26, v43
	v_mov_b32_e32 v27, v31
	v_pk_add_f32 v[24:25], v[26:27], v[24:25]
	s_mov_b32 s29, 0x800000
	v_add_f32_e32 v25, v25, v32
	v_add_f32_e32 v24, v24, v25
	v_mov_b32_e32 v25, v24
	s_nop 1
	v_permlane32_swap_b32_e32 v25, v24
	v_readlane_b32 s34, v254, 30
	v_readlane_b32 s35, v254, 31
	v_mov_b32_e32 v103, v65
	v_mov_b32_e32 v105, v65
	s_waitcnt lgkmcnt(0)
	v_add_f32_e32 v24, v24, v25
	v_mov_b32_e32 v25, v24
	s_nop 1
	v_permlane16_swap_b32_e32 v25, v24
	v_mov_b32_e32 v107, v65
	v_mov_b32_e32 v109, v65
	s_waitcnt lgkmcnt(0)
	v_add_f32_e32 v24, v24, v25
	s_nop 1
	v_mov_b32_dpp v25, v24 row_ror:8 row_mask:0xf bank_mask:0xf
	s_waitcnt lgkmcnt(0)
	v_add_f32_e32 v24, v24, v25
	s_nop 1
	v_mov_b32_dpp v25, v24 row_ror:4 row_mask:0xf bank_mask:0xf
	s_waitcnt lgkmcnt(0)
	v_add_f32_e32 v24, v24, v25
	s_nop 1
	v_mov_b32_dpp v25, v24 quad_perm:[2,3,0,1] row_mask:0xf bank_mask:0xf
	s_waitcnt lgkmcnt(0)
	v_add_f32_e32 v24, v24, v25
	s_nop 1
	v_mov_b32_dpp v25, v24 quad_perm:[1,0,3,2] row_mask:0xf bank_mask:0xf
	s_waitcnt lgkmcnt(0)
	v_add_f32_e32 v44, v24, v25
	v_fmamk_f32 v1, v44, 0xba000000, v1
	v_fmamk_f32 v5, v44, 0xba000000, v5
	v_fmac_f32_e32 v0, 0xba000000, v44
	v_mul_f32_e32 v24, v1, v1
	v_fmac_f32_e32 v4, 0xba000000, v44
	v_mul_f32_e32 v25, v5, v5
	v_fmamk_f32 v2, v44, 0xba000000, v2
	v_fmac_f32_e32 v24, v0, v0
	v_fmamk_f32 v6, v44, 0xba000000, v6
	v_fmac_f32_e32 v25, v4, v4
	v_fmamk_f32 v3, v44, 0xba000000, v3
	v_fmac_f32_e32 v24, v2, v2
	v_fmamk_f32 v7, v44, 0xba000000, v7
	v_fmac_f32_e32 v25, v6, v6
	v_fmac_f32_e32 v24, v3, v3
	v_fmac_f32_e32 v25, v7, v7
	v_fmamk_f32 v9, v44, 0xba000000, v9
	v_add_f32_e32 v24, v24, v25
	v_fmac_f32_e32 v8, 0xba000000, v44
	v_mul_f32_e32 v25, v9, v9
	v_fmamk_f32 v10, v44, 0xba000000, v10
	v_fmac_f32_e32 v25, v8, v8
	v_fmamk_f32 v11, v44, 0xba000000, v11
	v_fmac_f32_e32 v25, v10, v10
	v_fmac_f32_e32 v25, v11, v11
	v_fmamk_f32 v13, v44, 0xba000000, v13
	v_add_f32_e32 v24, v25, v24
	v_fmac_f32_e32 v12, 0xba000000, v44
	v_mul_f32_e32 v25, v13, v13
	v_fmamk_f32 v14, v44, 0xba000000, v14
	v_fmac_f32_e32 v25, v12, v12
	v_fmamk_f32 v15, v44, 0xba000000, v15
	v_fmac_f32_e32 v25, v14, v14
	v_fmamk_f32 v17, v44, 0xba000000, v17
	v_fmamk_f32 v21, v44, 0xba000000, v21
	v_fmac_f32_e32 v25, v15, v15
	v_fmac_f32_e32 v16, 0xba000000, v44
	v_fmac_f32_e32 v20, 0xba000000, v44
	v_mov_b32_e32 v26, v21
	v_mov_b32_e32 v27, v17
	v_add_f32_e32 v45, v25, v24
	v_mov_b32_e32 v24, v20
	v_mov_b32_e32 v25, v16
	v_pk_mul_f32 v[26:27], v[26:27], v[26:27]
	v_fmamk_f32 v18, v44, 0xba000000, v18
	v_pk_fma_f32 v[36:37], v[24:25], v[24:25], v[26:27]
	global_load_dwordx4 v[24:27], v[72:73], off
	global_load_dwordx4 v[32:35], v[74:75], off
	v_fmamk_f32 v22, v44, 0xba000000, v22
	v_fmamk_f32 v19, v44, 0xba000000, v19
	v_fmamk_f32 v23, v44, 0xba000000, v23
	v_mov_b32_e32 v38, v22
	v_mov_b32_e32 v39, v18
	v_pk_fma_f32 v[36:37], v[38:39], v[38:39], v[36:37]
	v_mov_b32_e32 v38, v23
	v_mov_b32_e32 v39, v19
	v_pk_fma_f32 v[36:37], v[38:39], v[38:39], v[36:37]
	v_fmamk_f32 v29, v44, 0xba000000, v29
	v_fmamk_f32 v41, v44, 0xba000000, v41
	v_add_f32_e32 v37, v37, v45
	v_fmac_f32_e32 v28, 0xba000000, v44
	v_fmac_f32_e32 v40, 0xba000000, v44
	v_mov_b32_e32 v38, v41
	v_mov_b32_e32 v39, v29
	v_add_f32_e32 v45, v36, v37
	v_fmamk_f32 v30, v44, 0xba000000, v30
	v_fmamk_f32 v42, v44, 0xba000000, v42
	v_mov_b32_e32 v36, v40
	v_mov_b32_e32 v37, v28
	v_pk_mul_f32 v[38:39], v[38:39], v[38:39]
	v_fmamk_f32 v31, v44, 0xba000000, v31
	v_fmamk_f32 v43, v44, 0xba000000, v43
	v_pk_fma_f32 v[36:37], v[36:37], v[36:37], v[38:39]
	v_mov_b32_e32 v38, v42
	v_mov_b32_e32 v39, v30
	v_pk_fma_f32 v[36:37], v[38:39], v[38:39], v[36:37]
	v_mov_b32_e32 v38, v43
	v_mov_b32_e32 v39, v31
	v_pk_fma_f32 v[36:37], v[38:39], v[38:39], v[36:37]
	v_lshlrev_b64 v[38:39], 13, v[114:115]
	v_add_f32_e32 v37, v37, v45
	v_add_f32_e32 v36, v36, v37
	v_mov_b32_e32 v37, v36
	s_nop 1
	v_permlane32_swap_b32_e32 v37, v36
	v_lshl_add_u64 v[38:39], s[34:35], 0, v[38:39]
	s_waitcnt lgkmcnt(0)
	v_add_f32_e32 v36, v36, v37
	v_mov_b32_e32 v37, v36
	s_nop 1
	v_permlane16_swap_b32_e32 v37, v36
	s_waitcnt lgkmcnt(0)
; __device__ __forceinline__ u32x2 pack4(f32x4 v) { u32x2 r; r[0] = cvt_pk(v[0], v[1]); r[1] = cvt_pk(v[2], v[3]); return r; }
; __device__ __forceinline__ void ln_finish_row(int r, int lane, f32x4 (&x)[8], float* dstf, bf16_t* dstb, const float* g, const float* bta) {
;     ...
;   const float rstd = rsqrtf(wave_sum(q) * (1.0f / 2048.0f) + LN_EPS);
; #pragma unroll
;   for (int k = 0; k < 8; ++k) {
;     const int col = 256 * k + 4 * lane;
;     const f32x4 gg = *(const f32x4*)(g + col), bb = *(const f32x4*)(bta + col);
;     const f32x4 y = x[k] * rstd * gg + bb;
;     *(f32x4*)(dstf + (size_t)r * 2048 + col) = y;
;     if (dstb) *(u32x2*)(dstb + (size_t)r * 2048 + col) = pack4(y);
;   }
	v_add_f32_e32 v36, v36, v37
	s_nop 1
	v_mov_b32_dpp v37, v36 row_ror:8 row_mask:0xf bank_mask:0xf
	s_waitcnt lgkmcnt(0)
	v_add_f32_e32 v36, v36, v37
	s_nop 1
	v_mov_b32_dpp v37, v36 row_ror:4 row_mask:0xf bank_mask:0xf
	s_waitcnt lgkmcnt(0)
	v_add_f32_e32 v36, v36, v37
	s_nop 1
	v_mov_b32_dpp v37, v36 quad_perm:[2,3,0,1] row_mask:0xf bank_mask:0xf
	s_waitcnt lgkmcnt(0)
	v_add_f32_e32 v36, v36, v37
	s_nop 1
	v_mov_b32_dpp v37, v36 quad_perm:[1,0,3,2] row_mask:0xf bank_mask:0xf
	s_waitcnt lgkmcnt(0)
	v_add_f32_e32 v36, v36, v37
	v_fmamk_f32 v36, v36, 0x3a000000, v228
	v_mul_f32_e32 v37, 0x4b800000, v36
	v_cmp_gt_f32_e32 vcc, s29, v36
	s_nop 1
	v_cndmask_b32_e32 v36, v36, v37, vcc
	v_rsq_f32_e32 v36, v36
	s_nop 0
	v_mul_f32_e32 v37, 0x45800000, v36
	v_cndmask_b32_e32 v36, v36, v37, vcc
	v_pk_mul_f32 v[44:45], v[0:1], v[36:37] op_sel_hi:[1,0]
	v_pk_mul_f32 v[46:47], v[2:3], v[36:37] op_sel_hi:[1,0]
	s_waitcnt vmcnt(0)
	v_pk_fma_f32 v[24:25], v[24:25], v[44:45], v[32:33]
	v_pk_fma_f32 v[26:27], v[26:27], v[46:47], v[34:35]
	v_lshl_add_u64 v[44:45], v[38:39], 0, v[64:65]
	global_store_dwordx4 v[44:45], v[24:27], off
	v_pk_mul_f32 v[48:49], v[6:7], v[36:37] op_sel_hi:[1,0]
	v_pk_mul_f32 v[50:51], v[4:5], v[36:37] op_sel_hi:[1,0]
	v_cvt_pk_bf16_f32 v24, v24, v25
	v_cvt_pk_bf16_f32 v25, v26, v27
	v_lshlrev_b64 v[26:27], 12, v[114:115]
	v_lshl_add_u64 v[46:47], v[94:95], 0, v[26:27]
	global_store_dwordx2 v[46:47], v[24:25], off
	global_load_dwordx4 v[24:27], v[72:73], off offset:1024
	s_nop 0
	global_load_dwordx4 v[32:35], v[74:75], off offset:1024
	s_waitcnt vmcnt(0)
	v_pk_fma_f32 v[24:25], v[24:25], v[50:51], v[32:33]
	v_pk_fma_f32 v[26:27], v[26:27], v[48:49], v[34:35]
	global_store_dwordx4 v[44:45], v[24:27], off offset:1024
	v_pk_mul_f32 v[48:49], v[10:11], v[36:37] op_sel_hi:[1,0]
	v_pk_mul_f32 v[50:51], v[8:9], v[36:37] op_sel_hi:[1,0]
	v_cvt_pk_bf16_f32 v24, v24, v25
	v_cvt_pk_bf16_f32 v25, v26, v27
	global_store_dwordx2 v[46:47], v[24:25], off offset:512
	global_load_dwordx4 v[24:27], v[72:73], off offset:2048
	s_nop 0
	global_load_dwordx4 v[32:35], v[74:75], off offset:2048
	s_waitcnt vmcnt(0)
	v_pk_fma_f32 v[24:25], v[24:25], v[50:51], v[32:33]
	v_pk_fma_f32 v[26:27], v[26:27], v[48:49], v[34:35]
	global_store_dwordx4 v[44:45], v[24:27], off offset:2048
	v_pk_mul_f32 v[48:49], v[14:15], v[36:37] op_sel_hi:[1,0]
	v_pk_mul_f32 v[50:51], v[12:13], v[36:37] op_sel_hi:[1,0]
	v_cvt_pk_bf16_f32 v24, v24, v25
	v_cvt_pk_bf16_f32 v25, v26, v27
	global_store_dwordx2 v[46:47], v[24:25], off offset:1024
	global_load_dwordx4 v[24:27], v[72:73], off offset:3072
	s_nop 0
	global_load_dwordx4 v[32:35], v[74:75], off offset:3072
	s_waitcnt vmcnt(0)
	v_pk_fma_f32 v[24:25], v[24:25], v[50:51], v[32:33]
	v_pk_fma_f32 v[26:27], v[26:27], v[48:49], v[34:35]
	global_store_dwordx4 v[44:45], v[24:27], off offset:3072
	v_pk_mul_f32 v[48:49], v[18:19], v[36:37] op_sel_hi:[1,0]
	v_pk_mul_f32 v[50:51], v[16:17], v[36:37] op_sel_hi:[1,0]
	v_cvt_pk_bf16_f32 v24, v24, v25
	v_cvt_pk_bf16_f32 v25, v26, v27
	global_store_dwordx2 v[46:47], v[24:25], off offset:1536
	global_load_dwordx4 v[24:27], v[76:77], off
	s_nop 0
	global_load_dwordx4 v[32:35], v[78:79], off
	v_lshl_add_u64 v[44:45], v[38:39], 0, v[102:103]
	s_waitcnt vmcnt(0)
	v_pk_fma_f32 v[24:25], v[24:25], v[50:51], v[32:33]
	v_pk_fma_f32 v[26:27], v[26:27], v[48:49], v[34:35]
	global_store_dwordx4 v[44:45], v[24:27], off
	v_pk_mul_f32 v[48:49], v[22:23], v[36:37] op_sel_hi:[1,0]
	v_pk_mul_f32 v[50:51], v[20:21], v[36:37] op_sel_hi:[1,0]
	v_cvt_pk_bf16_f32 v24, v24, v25
	v_cvt_pk_bf16_f32 v25, v26, v27
	global_store_dwordx2 v[46:47], v[24:25], off offset:2048
	global_load_dwordx4 v[24:27], v[80:81], off
	s_nop 0
	global_load_dwordx4 v[32:35], v[82:83], off
	v_lshl_add_u64 v[44:45], v[38:39], 0, v[104:105]
	s_waitcnt vmcnt(0)
	v_pk_fma_f32 v[24:25], v[24:25], v[50:51], v[32:33]
	v_pk_fma_f32 v[26:27], v[26:27], v[48:49], v[34:35]
	global_store_dwordx4 v[44:45], v[24:27], off
	v_pk_mul_f32 v[48:49], v[30:31], v[36:37] op_sel_hi:[1,0]
	v_pk_mul_f32 v[50:51], v[28:29], v[36:37] op_sel_hi:[1,0]
	v_cvt_pk_bf16_f32 v24, v24, v25
	v_cvt_pk_bf16_f32 v25, v26, v27
	global_store_dwordx2 v[46:47], v[24:25], off offset:2560
	global_load_dwordx4 v[24:27], v[84:85], off
	s_nop 0
	global_load_dwordx4 v[32:35], v[86:87], off
	v_lshl_add_u64 v[44:45], v[38:39], 0, v[106:107]
	v_lshl_add_u64 v[38:39], v[38:39], 0, v[108:109]
	s_waitcnt vmcnt(0)
	v_pk_fma_f32 v[24:25], v[24:25], v[50:51], v[32:33]
	v_pk_fma_f32 v[26:27], v[26:27], v[48:49], v[34:35]
	global_store_dwordx4 v[44:45], v[24:27], off
	v_pk_mul_f32 v[44:45], v[42:43], v[36:37] op_sel_hi:[1,0]
	v_pk_mul_f32 v[36:37], v[40:41], v[36:37] op_sel_hi:[1,0]
	v_cvt_pk_bf16_f32 v24, v24, v25
	v_cvt_pk_bf16_f32 v25, v26, v27
	global_store_dwordx2 v[46:47], v[24:25], off offset:3072
	global_load_dwordx4 v[24:27], v[88:89], off
	s_nop 0
	global_load_dwordx4 v[32:35], v[90:91], off
	s_waitcnt vmcnt(0)
	v_pk_fma_f32 v[24:25], v[36:37], v[24:25], v[32:33]
	v_pk_fma_f32 v[26:27], v[44:45], v[26:27], v[34:35]
	global_store_dwordx4 v[38:39], v[24:27], off
	s_nop 1
	v_cvt_pk_bf16_f32 v24, v24, v25
	v_cvt_pk_bf16_f32 v25, v26, v27
	global_store_dwordx2 v[46:47], v[24:25], off offset:3584
	s_branch .LBB0_91

; __device__ __forceinline__ u32x2 pack4(f32x4 v) { u32x2 r; r[0] = cvt_pk(v[0], v[1]); r[1] = cvt_pk(v[2], v[3]); return r; }
; __device__ __forceinline__ f32x4 unpack4(u32x2 u) { f32x4 r; r[0] = bflo(u[0]); r[1] = bfhi(u[0]); r[2] = bflo(u[1]); r[3] = bfhi(u[1]); return r; }
; __device__ __forceinline__ float wave_sum(float v) {
; #pragma unroll
;   for (int o = 32; o >= 1; o >>= 1) v += __shfl_xor(v, o);
;   return v;
; }
; __device__ __forceinline__ void phase_retpost(const Params& p) {
;     ...
;   for (int pr0 = (blockIdx.x * 8 + w) * 8; pr0 < TOKP * 8; pr0 += gridDim.x * 8 * 8) {
;     u32x2 xr[8], sr[8];
; #pragma unroll
;     for (int q = 0; q < 8; ++q) {
;       const int pr = pr0 + q, r = pr >> 3, h = pr & 7;
;       const size_t o = (size_t)r * 2048 + h * 256 + 4 * lane;
;       xr[q] = *(const u32x2*)(RO + o);
;       sr[q] = *(const u32x2*)(RG + o);
;     }
; #pragma unroll
;     for (int q = 0; q < 8; ++q) {
;       const int pr = pr0 + q, r = pr >> 3, h = pr & 7;
;       const f32x4 x = unpack4(xr[q]);
;       const float mean = wave_sum(x[0] + x[1] + x[2] + x[3]) * (1.0f / 256.0f);
;       const f32x4 d = x - mean;
;       const float var = wave_sum(d[0] * d[0] + d[1] * d[1] + d[2] * d[2] + d[3] * d[3]) * (1.0f / 256.0f);
;       const float rstd = rsqrtf(var + LN_EPS);
;       const f32x4 gn = *(const f32x4*)(p.in[12] + h * 256 + 4 * lane);
;       const f32x4 sg = unpack4(sr[q]);
;       *(u32x2*)(ACAT + (size_t)r * 4096 + 1024 + h * 256 + 4 * lane) = pack4(d * rstd * gn * sg);
.LBB0_174:
	v_ashrrev_i32_e32 v0, 3, v62
	v_ashrrev_i32_e32 v1, 31, v0
	v_lshlrev_b64 v[2:3], 12, v[0:1]
	v_or_b32_e32 v2, v2, v64
	v_lshl_add_u64 v[14:15], s[94:95], 0, v[2:3]
	global_load_dwordx2 v[46:47], v[14:15], off
	v_lshl_add_u64 v[14:15], s[60:61], 0, v[2:3]
	global_load_dwordx2 v[24:25], v[14:15], off
	v_or_b32_e32 v14, 0x200, v2
	v_mov_b32_e32 v15, v3
	v_lshl_add_u64 v[16:17], s[94:95], 0, v[14:15]
	global_load_dwordx2 v[48:49], v[16:17], off
	v_lshlrev_b64 v[0:1], 13, v[0:1]
	v_lshl_add_u64 v[0:1], s[24:25], 0, v[0:1]
	v_lshl_add_u64 v[44:45], v[0:1], 0, v[64:65]
	v_lshl_add_u64 v[14:15], s[60:61], 0, v[14:15]
	global_load_dwordx2 v[42:43], v[14:15], off
	v_or_b32_e32 v14, 0x400, v2
	v_mov_b32_e32 v15, v3
	v_lshl_add_u64 v[16:17], s[94:95], 0, v[14:15]
	v_lshl_add_u64 v[14:15], s[60:61], 0, v[14:15]
	global_load_dwordx2 v[40:41], v[16:17], off
	global_load_dwordx2 v[36:37], v[14:15], off
	v_or_b32_e32 v14, 0x600, v2
	v_mov_b32_e32 v15, v3
	v_lshl_add_u64 v[16:17], s[94:95], 0, v[14:15]
	v_lshl_add_u64 v[14:15], s[60:61], 0, v[14:15]
	global_load_dwordx2 v[38:39], v[16:17], off
	global_load_dwordx2 v[34:35], v[14:15], off
	v_or_b32_e32 v14, 0x800, v2
	v_mov_b32_e32 v15, v3
	v_lshl_add_u64 v[16:17], s[94:95], 0, v[14:15]
	v_lshl_add_u64 v[14:15], s[60:61], 0, v[14:15]
	global_load_dwordx2 v[32:33], v[16:17], off
	global_load_dwordx2 v[28:29], v[14:15], off
	v_or_b32_e32 v14, 0xa00, v2
	v_mov_b32_e32 v15, v3
	v_lshl_add_u64 v[16:17], s[94:95], 0, v[14:15]
	v_lshl_add_u64 v[14:15], s[60:61], 0, v[14:15]
	global_load_dwordx2 v[30:31], v[16:17], off
	global_load_dwordx2 v[26:27], v[14:15], off
	v_or_b32_e32 v14, 0xc00, v2
	v_mov_b32_e32 v15, v3
	v_lshl_add_u64 v[16:17], s[94:95], 0, v[14:15]
	v_lshl_add_u64 v[14:15], s[60:61], 0, v[14:15]
	v_or_b32_e32 v2, 0xe00, v2
	global_load_dwordx2 v[20:21], v[14:15], off
	v_lshl_add_u64 v[14:15], s[94:95], 0, v[2:3]
	v_lshl_add_u64 v[2:3], s[60:61], 0, v[2:3]
	global_load_dwordx2 v[22:23], v[16:17], off
	global_load_dwordx2 v[18:19], v[14:15], off
	s_mov_b32 s36, 0x3727c5ac
	global_load_dwordx2 v[14:15], v[2:3], off
	s_mov_b64 s[34:35], 0x109800
	v_lshl_add_u64 v[16:17], v[44:45], 0, s[34:35]
	v_add_u32_e32 v62, s62, v62
	s_mov_b32 s29, 0xffff
	s_waitcnt vmcnt(0)
	v_lshlrev_b32_e32 v50, 16, v46
	v_and_b32_e32 v51, 0xffff0000, v46
	v_lshlrev_b32_e32 v52, 16, v47
	v_add_f32_e32 v0, v50, v51
	v_and_b32_e32 v53, 0xffff0000, v47
	v_add_f32_e32 v0, v0, v52
	v_add_f32_e32 v0, v0, v53
	v_mov_b32_e32 v1, v0
	s_nop 1
	v_permlane32_swap_b32_e32 v1, v0
	s_waitcnt vmcnt(13)
	v_lshlrev_b32_e32 v46, 16, v48
	v_and_b32_e32 v47, 0xffff0000, v48
	v_lshlrev_b32_e32 v54, 16, v24
	v_and_b32_e32 v55, 0xffff0000, v24
	s_waitcnt lgkmcnt(0)
	v_add_f32_e32 v0, v0, v1
	v_mov_b32_e32 v1, v0
	s_nop 1
	v_permlane16_swap_b32_e32 v1, v0
	v_lshlrev_b32_e32 v48, 16, v49
	v_add_f32_e32 v24, v46, v47
	v_and_b32_e32 v49, 0xffff0000, v49
	v_add_f32_e32 v24, v24, v48
	s_waitcnt lgkmcnt(0)
	v_add_f32_e32 v0, v0, v1
	s_nop 1
	v_mov_b32_dpp v1, v0 row_ror:8 row_mask:0xf bank_mask:0xf
	v_add_f32_e32 v24, v24, v49
	v_lshlrev_b32_e32 v56, 16, v25
	v_and_b32_e32 v57, 0xffff0000, v25
	v_mov_b32_e32 v25, v24
	s_nop 1
	v_permlane32_swap_b32_e32 v25, v24
	s_waitcnt lgkmcnt(0)
	v_add_f32_e32 v0, v0, v1
	s_nop 1
	v_mov_b32_dpp v1, v0 row_ror:4 row_mask:0xf bank_mask:0xf
	s_waitcnt lgkmcnt(0)
	v_add_f32_e32 v24, v24, v25
	v_mov_b32_e32 v25, v24
	s_nop 1
	v_permlane16_swap_b32_e32 v25, v24
	s_waitcnt lgkmcnt(0)
	v_add_f32_e32 v0, v0, v1
	s_nop 1
	v_mov_b32_dpp v1, v0 quad_perm:[2,3,0,1] row_mask:0xf bank_mask:0xf
	s_waitcnt lgkmcnt(0)
	v_add_f32_e32 v24, v24, v25
	s_nop 1
	v_mov_b32_dpp v25, v24 row_ror:8 row_mask:0xf bank_mask:0xf
	s_waitcnt lgkmcnt(0)
	v_add_f32_e32 v0, v0, v1
	s_nop 1
	v_mov_b32_dpp v1, v0 quad_perm:[1,0,3,2] row_mask:0xf bank_mask:0xf
	s_waitcnt lgkmcnt(0)
	v_add_f32_e32 v24, v24, v25
	s_nop 1
	v_mov_b32_dpp v25, v24 row_ror:4 row_mask:0xf bank_mask:0xf
	s_waitcnt lgkmcnt(0)
	v_add_f32_e32 v0, v0, v1
	v_fmac_f32_e32 v51, 0xbb800000, v0
	v_fmac_f32_e32 v50, 0xbb800000, v0
	v_fmac_f32_e32 v53, 0xbb800000, v0
	v_fmac_f32_e32 v52, 0xbb800000, v0
	global_load_dwordx4 v[0:3], v[4:5], off
	s_waitcnt lgkmcnt(0)
	v_add_f32_e32 v24, v24, v25
	s_nop 1
	v_mov_b32_dpp v25, v24 quad_perm:[2,3,0,1] row_mask:0xf bank_mask:0xf
	v_pk_mul_f32 v[60:61], v[50:51], v[50:51]
	v_pk_mul_f32 v[58:59], v[52:53], v[52:53]
	v_mov_b32_e32 v75, v60
	s_waitcnt lgkmcnt(0)
	v_add_f32_e32 v24, v24, v25
	s_nop 1
	v_mov_b32_dpp v25, v24 quad_perm:[1,0,3,2] row_mask:0xf bank_mask:0xf
	s_waitcnt lgkmcnt(0)
	v_add_f32_e32 v24, v24, v25
	v_fmac_f32_e32 v47, 0xbb800000, v24
	v_fmac_f32_e32 v46, 0xbb800000, v24
	v_fmac_f32_e32 v49, 0xbb800000, v24
	v_fmac_f32_e32 v48, 0xbb800000, v24
	v_pk_mul_f32 v[72:73], v[46:47], v[46:47]
	v_pk_mul_f32 v[24:25], v[48:49], v[48:49]
	v_mov_b32_e32 v74, v72
	v_mov_b32_e32 v60, v73
	v_pk_add_f32 v[60:61], v[74:75], v[60:61]
	v_mov_b32_e32 v72, v24
	v_mov_b32_e32 v73, v58
	v_pk_add_f32 v[60:61], v[72:73], v[60:61]
	v_mov_b32_e32 v58, v25
	v_pk_add_f32 v[24:25], v[58:59], v[60:61]
	v_mov_b32_e32 v59, v25
	s_nop 1
	v_permlane32_swap_b32_e32 v59, v25
	v_mov_b32_e32 v58, v24
	s_nop 1
	v_permlane32_swap_b32_e32 v58, v24
	s_waitcnt lgkmcnt(0)
	v_pk_add_f32 v[24:25], v[24:25], v[58:59]
	v_mov_b32_e32 v59, v25
	s_nop 1
	v_permlane16_swap_b32_e32 v59, v25
	v_mov_b32_e32 v58, v24
	s_nop 1
	v_permlane16_swap_b32_e32 v58, v24
	s_waitcnt lgkmcnt(0)
	v_pk_add_f32 v[24:25], v[24:25], v[58:59]
	s_nop 1
	v_mov_b32_dpp v59, v25 row_ror:8 row_mask:0xf bank_mask:0xf
	s_nop 1
	v_mov_b32_dpp v58, v24 row_ror:8 row_mask:0xf bank_mask:0xf
	s_waitcnt lgkmcnt(0)
; __device__ __forceinline__ u32x2 pack4(f32x4 v) { u32x2 r; r[0] = cvt_pk(v[0], v[1]); r[1] = cvt_pk(v[2], v[3]); return r; }
; __device__ __forceinline__ f32x4 unpack4(u32x2 u) { f32x4 r; r[0] = bflo(u[0]); r[1] = bfhi(u[0]); r[2] = bflo(u[1]); r[3] = bfhi(u[1]); return r; }
; __device__ __forceinline__ void phase_retpost(const Params& p) {
;     ...
;     for (int q = 0; q < 8; ++q) {
;       const int pr = pr0 + q, r = pr >> 3, h = pr & 7;
;       const f32x4 x = unpack4(xr[q]);
;       const float mean = wave_sum(x[0] + x[1] + x[2] + x[3]) * (1.0f / 256.0f);
;       const f32x4 d = x - mean;
;       const float var = wave_sum(d[0] * d[0] + d[1] * d[1] + d[2] * d[2] + d[3] * d[3]) * (1.0f / 256.0f);
;       const float rstd = rsqrtf(var + LN_EPS);
;       const f32x4 gn = *(const f32x4*)(p.in[12] + h * 256 + 4 * lane);
;       const f32x4 sg = unpack4(sr[q]);
;       *(u32x2*)(ACAT + (size_t)r * 4096 + 1024 + h * 256 + 4 * lane) = pack4(d * rstd * gn * sg);
	v_pk_add_f32 v[24:25], v[24:25], v[58:59]
	s_nop 1
	v_mov_b32_dpp v59, v25 row_ror:4 row_mask:0xf bank_mask:0xf
	s_nop 1
	v_mov_b32_dpp v58, v24 row_ror:4 row_mask:0xf bank_mask:0xf
	s_waitcnt lgkmcnt(0)
	v_pk_add_f32 v[24:25], v[24:25], v[58:59]
	s_nop 1
	v_mov_b32_dpp v59, v25 quad_perm:[2,3,0,1] row_mask:0xf bank_mask:0xf
	s_nop 1
	v_mov_b32_dpp v58, v24 quad_perm:[2,3,0,1] row_mask:0xf bank_mask:0xf
	s_waitcnt lgkmcnt(0)
	v_pk_add_f32 v[24:25], v[24:25], v[58:59]
	s_nop 1
	v_mov_b32_dpp v59, v25 quad_perm:[1,0,3,2] row_mask:0xf bank_mask:0xf
	s_nop 1
	v_mov_b32_dpp v58, v24 quad_perm:[1,0,3,2] row_mask:0xf bank_mask:0xf
	s_waitcnt lgkmcnt(0)
	v_pk_add_f32 v[58:59], v[24:25], v[58:59]
	v_mov_b64_e32 v[24:25], s[36:37]
	v_pk_fma_f32 v[58:59], v[58:59], s[30:31], v[24:25] op_sel_hi:[1,0,0]
	s_nop 0
	v_mul_f32_e32 v60, 0x4b800000, v59
	v_cmp_gt_f32_e64 s[36:37], s66, v59
	v_cmp_gt_f32_e32 vcc, s66, v58
	s_nop 0
	v_cndmask_b32_e64 v59, v59, v60, s[36:37]
	v_rsq_f32_e32 v59, v59
	s_nop 0
	v_mul_f32_e32 v60, 0x45800000, v59
	v_cndmask_b32_e64 v60, v59, v60, s[36:37]
	v_pk_mul_f32 v[52:53], v[52:53], v[60:61] op_sel_hi:[1,0]
	v_pk_mul_f32 v[50:51], v[50:51], v[60:61] op_sel_hi:[1,0]
	s_waitcnt vmcnt(0)
	v_pk_mul_f32 v[2:3], v[2:3], v[52:53]
	v_pk_mul_f32 v[0:1], v[0:1], v[50:51]
	v_pk_mul_f32 v[2:3], v[2:3], v[56:57]
	v_pk_mul_f32 v[0:1], v[0:1], v[54:55]
	v_lshlrev_b32_e32 v50, 16, v42
	v_cvt_pk_bf16_f32 v0, v0, v1
	v_cvt_pk_bf16_f32 v1, v2, v3
	v_add_co_u32_e64 v2, s[36:37], s63, v44
	v_and_b32_e32 v51, 0xffff0000, v42
	s_nop 0
	v_addc_co_u32_e64 v3, s[36:37], 0, v45, s[36:37]
	global_store_dwordx2 v[2:3], v[0:1], off offset:2048
	v_mul_f32_e32 v0, 0x4b800000, v58
	v_cndmask_b32_e32 v0, v58, v0, vcc
	v_rsq_f32_e32 v0, v0
	v_lshlrev_b32_e32 v42, 16, v43
	v_and_b32_e32 v43, 0xffff0000, v43
	v_mul_f32_e32 v1, 0x45800000, v0
	v_cndmask_b32_e32 v44, v0, v1, vcc
	global_load_dwordx4 v[0:3], v[4:5], off offset:1024
	v_pk_mul_f32 v[48:49], v[48:49], v[44:45] op_sel_hi:[1,0]
	v_pk_mul_f32 v[44:45], v[46:47], v[44:45] op_sel_hi:[1,0]
	s_waitcnt vmcnt(0)
	v_pk_mul_f32 v[2:3], v[2:3], v[48:49]
	v_pk_mul_f32 v[0:1], v[0:1], v[44:45]
	v_pk_mul_f32 v[2:3], v[2:3], v[42:43]
	v_pk_mul_f32 v[0:1], v[0:1], v[50:51]
	v_lshlrev_b32_e32 v42, 16, v40
	v_cvt_pk_bf16_f32 v0, v0, v1
	v_cvt_pk_bf16_f32 v1, v2, v3
	v_and_b32_e32 v43, 0xffff0000, v40
	global_store_dwordx2 v[16:17], v[0:1], off offset:512
	v_lshlrev_b32_e32 v40, 16, v41
	v_add_f32_e32 v0, v42, v43
	v_and_b32_e32 v41, 0xffff0000, v41
	v_add_f32_e32 v0, v0, v40
	v_add_f32_e32 v0, v0, v41
	v_mov_b32_e32 v1, v0
	s_nop 1
	v_permlane32_swap_b32_e32 v1, v0
	v_lshlrev_b32_e32 v48, 16, v36
	v_and_b32_e32 v49, 0xffff0000, v36
	v_lshlrev_b32_e32 v50, 16, v37
	v_and_b32_e32 v51, 0xffff0000, v37
	s_waitcnt lgkmcnt(0)
	v_add_f32_e32 v0, v0, v1
	v_mov_b32_e32 v1, v0
	s_nop 1
	v_permlane16_swap_b32_e32 v1, v0
	v_lshlrev_b32_e32 v36, 16, v38
	v_and_b32_e32 v37, 0xffff0000, v38
	v_lshlrev_b32_e32 v38, 16, v39
	v_add_f32_e32 v52, v36, v37
	s_waitcnt lgkmcnt(0)
	v_add_f32_e32 v0, v0, v1
	s_nop 1
	v_mov_b32_dpp v1, v0 row_ror:8 row_mask:0xf bank_mask:0xf
	v_and_b32_e32 v39, 0xffff0000, v39
	v_add_f32_e32 v52, v52, v38
	v_add_f32_e32 v52, v52, v39
	v_mov_b32_e32 v53, v52
	s_nop 1
	v_permlane32_swap_b32_e32 v53, v52
	s_waitcnt lgkmcnt(0)
	v_add_f32_e32 v0, v0, v1
	s_nop 1
	v_mov_b32_dpp v1, v0 row_ror:4 row_mask:0xf bank_mask:0xf
	s_waitcnt lgkmcnt(0)
	v_add_f32_e32 v52, v52, v53
	v_mov_b32_e32 v53, v52
	s_nop 1
	v_permlane16_swap_b32_e32 v53, v52
	s_waitcnt lgkmcnt(0)
	v_add_f32_e32 v0, v0, v1
	s_nop 1
	v_mov_b32_dpp v1, v0 quad_perm:[2,3,0,1] row_mask:0xf bank_mask:0xf
	s_waitcnt lgkmcnt(0)
	v_add_f32_e32 v52, v52, v53
	s_nop 1
	v_mov_b32_dpp v53, v52 row_ror:8 row_mask:0xf bank_mask:0xf
	s_waitcnt lgkmcnt(0)
	v_add_f32_e32 v0, v0, v1
	s_nop 1
	v_mov_b32_dpp v1, v0 quad_perm:[1,0,3,2] row_mask:0xf bank_mask:0xf
	s_waitcnt lgkmcnt(0)
	v_add_f32_e32 v52, v52, v53
	s_nop 1
	v_mov_b32_dpp v53, v52 row_ror:4 row_mask:0xf bank_mask:0xf
	s_waitcnt lgkmcnt(0)
	v_add_f32_e32 v0, v0, v1
	v_fmac_f32_e32 v43, 0xbb800000, v0
	v_fmac_f32_e32 v42, 0xbb800000, v0
	v_fmac_f32_e32 v41, 0xbb800000, v0
	v_fmac_f32_e32 v40, 0xbb800000, v0
	global_load_dwordx4 v[0:3], v[4:5], off offset:2048
	s_waitcnt lgkmcnt(0)
	v_add_f32_e32 v52, v52, v53
	s_nop 1
	v_mov_b32_dpp v53, v52 quad_perm:[2,3,0,1] row_mask:0xf bank_mask:0xf
	v_pk_mul_f32 v[46:47], v[42:43], v[42:43]
	v_pk_mul_f32 v[44:45], v[40:41], v[40:41]
	v_mov_b32_e32 v57, v46
	s_waitcnt lgkmcnt(0)
	v_add_f32_e32 v52, v52, v53
	s_nop 1
	v_mov_b32_dpp v53, v52 quad_perm:[1,0,3,2] row_mask:0xf bank_mask:0xf
	s_waitcnt lgkmcnt(0)
	v_add_f32_e32 v52, v52, v53
	v_fmac_f32_e32 v37, 0xbb800000, v52
	v_fmac_f32_e32 v36, 0xbb800000, v52
	v_fmac_f32_e32 v39, 0xbb800000, v52
	v_fmac_f32_e32 v38, 0xbb800000, v52
	v_pk_mul_f32 v[54:55], v[36:37], v[36:37]
	v_pk_mul_f32 v[52:53], v[38:39], v[38:39]
	v_mov_b32_e32 v56, v54
	v_mov_b32_e32 v46, v55
	v_pk_add_f32 v[46:47], v[56:57], v[46:47]
	v_mov_b32_e32 v54, v52
	v_mov_b32_e32 v55, v44
	v_pk_add_f32 v[46:47], v[54:55], v[46:47]
	v_mov_b32_e32 v44, v53
	v_pk_add_f32 v[44:45], v[44:45], v[46:47]
	v_mov_b32_e32 v47, v45
	s_nop 1
	v_permlane32_swap_b32_e32 v47, v45
	v_mov_b32_e32 v46, v44
	s_nop 1
	v_permlane32_swap_b32_e32 v46, v44
	s_waitcnt lgkmcnt(0)
	v_pk_add_f32 v[44:45], v[44:45], v[46:47]
	v_mov_b32_e32 v47, v45
	s_nop 1
	v_permlane16_swap_b32_e32 v47, v45
	v_mov_b32_e32 v46, v44
	s_nop 1
	v_permlane16_swap_b32_e32 v46, v44
	s_waitcnt lgkmcnt(0)
	v_pk_add_f32 v[44:45], v[44:45], v[46:47]
	s_nop 1
	v_mov_b32_dpp v47, v45 row_ror:8 row_mask:0xf bank_mask:0xf
	s_nop 1
	v_mov_b32_dpp v46, v44 row_ror:8 row_mask:0xf bank_mask:0xf
	s_waitcnt lgkmcnt(0)
; __device__ __forceinline__ u32x2 pack4(f32x4 v) { u32x2 r; r[0] = cvt_pk(v[0], v[1]); r[1] = cvt_pk(v[2], v[3]); return r; }
; __device__ __forceinline__ f32x4 unpack4(u32x2 u) { f32x4 r; r[0] = bflo(u[0]); r[1] = bfhi(u[0]); r[2] = bflo(u[1]); r[3] = bfhi(u[1]); return r; }
; __device__ __forceinline__ void phase_retpost(const Params& p) {
;     ...
;     for (int q = 0; q < 8; ++q) {
;       const int pr = pr0 + q, r = pr >> 3, h = pr & 7;
;       const f32x4 x = unpack4(xr[q]);
;       const float mean = wave_sum(x[0] + x[1] + x[2] + x[3]) * (1.0f / 256.0f);
;       const f32x4 d = x - mean;
;       const float var = wave_sum(d[0] * d[0] + d[1] * d[1] + d[2] * d[2] + d[3] * d[3]) * (1.0f / 256.0f);
;       const float rstd = rsqrtf(var + LN_EPS);
;       const f32x4 gn = *(const f32x4*)(p.in[12] + h * 256 + 4 * lane);
;       const f32x4 sg = unpack4(sr[q]);
;       *(u32x2*)(ACAT + (size_t)r * 4096 + 1024 + h * 256 + 4 * lane) = pack4(d * rstd * gn * sg);
	v_pk_add_f32 v[44:45], v[44:45], v[46:47]
	s_nop 1
	v_mov_b32_dpp v47, v45 row_ror:4 row_mask:0xf bank_mask:0xf
	s_nop 1
	v_mov_b32_dpp v46, v44 row_ror:4 row_mask:0xf bank_mask:0xf
	s_waitcnt lgkmcnt(0)
	v_pk_add_f32 v[44:45], v[44:45], v[46:47]
	s_nop 1
	v_mov_b32_dpp v47, v45 quad_perm:[2,3,0,1] row_mask:0xf bank_mask:0xf
	s_nop 1
	v_mov_b32_dpp v46, v44 quad_perm:[2,3,0,1] row_mask:0xf bank_mask:0xf
	s_waitcnt lgkmcnt(0)
	v_pk_add_f32 v[44:45], v[44:45], v[46:47]
	s_nop 1
	v_mov_b32_dpp v47, v45 quad_perm:[1,0,3,2] row_mask:0xf bank_mask:0xf
	s_nop 1
	v_mov_b32_dpp v46, v44 quad_perm:[1,0,3,2] row_mask:0xf bank_mask:0xf
	s_waitcnt lgkmcnt(0)
	v_pk_add_f32 v[44:45], v[44:45], v[46:47]
	s_nop 0
	v_pk_fma_f32 v[44:45], v[44:45], s[30:31], v[24:25] op_sel_hi:[1,0,0]
	s_nop 0
	v_mul_f32_e32 v46, 0x4b800000, v45
	v_cmp_gt_f32_e64 s[36:37], s66, v45
	v_cmp_gt_f32_e32 vcc, s66, v44
	s_nop 0
	v_cndmask_b32_e64 v45, v45, v46, s[36:37]
	v_rsq_f32_e32 v45, v45
	s_nop 0
	v_mul_f32_e32 v46, 0x45800000, v45
	v_cndmask_b32_e64 v46, v45, v46, s[36:37]
	v_pk_mul_f32 v[40:41], v[40:41], v[46:47] op_sel_hi:[1,0]
	v_pk_mul_f32 v[42:43], v[42:43], v[46:47] op_sel_hi:[1,0]
	s_waitcnt vmcnt(0)
	v_pk_mul_f32 v[2:3], v[2:3], v[40:41]
	v_pk_mul_f32 v[0:1], v[0:1], v[42:43]
	v_pk_mul_f32 v[2:3], v[2:3], v[50:51]
	v_pk_mul_f32 v[0:1], v[0:1], v[48:49]
	v_lshlrev_b32_e32 v42, 16, v34
	v_cvt_pk_bf16_f32 v0, v0, v1
	v_cvt_pk_bf16_f32 v1, v2, v3
	global_store_dwordx2 v[16:17], v[0:1], off offset:1024
	v_mul_f32_e32 v0, 0x4b800000, v44
	v_cndmask_b32_e32 v0, v44, v0, vcc
	v_rsq_f32_e32 v0, v0
	v_and_b32_e32 v43, 0xffff0000, v34
	v_lshlrev_b32_e32 v34, 16, v35
	v_and_b32_e32 v35, 0xffff0000, v35
	v_mul_f32_e32 v1, 0x45800000, v0
	v_cndmask_b32_e32 v40, v0, v1, vcc
	global_load_dwordx4 v[0:3], v[4:5], off offset:3072
	v_pk_mul_f32 v[38:39], v[38:39], v[40:41] op_sel_hi:[1,0]
	v_pk_mul_f32 v[36:37], v[36:37], v[40:41] op_sel_hi:[1,0]
	v_lshlrev_b32_e32 v40, 16, v28
	v_and_b32_e32 v41, 0xffff0000, v28
	v_lshlrev_b32_e32 v28, 16, v30
	s_waitcnt vmcnt(0)
	v_pk_mul_f32 v[0:1], v[0:1], v[36:37]
	v_pk_mul_f32 v[2:3], v[2:3], v[38:39]
	v_pk_mul_f32 v[0:1], v[0:1], v[42:43]
	v_pk_mul_f32 v[2:3], v[2:3], v[34:35]
	v_cvt_pk_bf16_f32 v0, v0, v1
	v_cvt_pk_bf16_f32 v1, v2, v3
	v_lshlrev_b32_e32 v34, 16, v32
	v_and_b32_e32 v35, 0xffff0000, v32
	global_store_dwordx2 v[16:17], v[0:1], off offset:1536
	v_lshlrev_b32_e32 v32, 16, v33
	v_add_f32_e32 v0, v34, v35
	v_and_b32_e32 v33, 0xffff0000, v33
	v_add_f32_e32 v0, v0, v32
	v_add_f32_e32 v0, v0, v33
	v_mov_b32_e32 v1, v0
	s_nop 1
	v_permlane32_swap_b32_e32 v1, v0
	v_lshlrev_b32_e32 v42, 16, v29
	v_and_b32_e32 v43, 0xffff0000, v29
	v_and_b32_e32 v29, 0xffff0000, v30
	v_lshlrev_b32_e32 v30, 16, v31
	s_waitcnt lgkmcnt(0)
	v_add_f32_e32 v0, v0, v1
	v_mov_b32_e32 v1, v0
	s_nop 1
	v_permlane16_swap_b32_e32 v1, v0
	v_add_f32_e32 v44, v28, v29
	v_and_b32_e32 v31, 0xffff0000, v31
	v_add_f32_e32 v44, v44, v30
	v_add_f32_e32 v44, v44, v31
	s_waitcnt lgkmcnt(0)
	v_add_f32_e32 v0, v0, v1
	s_nop 1
	v_mov_b32_dpp v1, v0 row_ror:8 row_mask:0xf bank_mask:0xf
	v_mov_b32_e32 v45, v44
	s_nop 1
	v_permlane32_swap_b32_e32 v45, v44
	s_waitcnt lgkmcnt(0)
	v_add_f32_e32 v0, v0, v1
	s_nop 1
	v_mov_b32_dpp v1, v0 row_ror:4 row_mask:0xf bank_mask:0xf
	s_waitcnt lgkmcnt(0)
	v_add_f32_e32 v44, v44, v45
	v_mov_b32_e32 v45, v44
	s_nop 1
	v_permlane16_swap_b32_e32 v45, v44
	s_waitcnt lgkmcnt(0)
	v_add_f32_e32 v0, v0, v1
	s_nop 1
	v_mov_b32_dpp v1, v0 quad_perm:[2,3,0,1] row_mask:0xf bank_mask:0xf
	s_waitcnt lgkmcnt(0)
	v_add_f32_e32 v44, v44, v45
	s_nop 1
	v_mov_b32_dpp v45, v44 row_ror:8 row_mask:0xf bank_mask:0xf
	s_waitcnt lgkmcnt(0)
	v_add_f32_e32 v0, v0, v1
	s_nop 1
	v_mov_b32_dpp v1, v0 quad_perm:[1,0,3,2] row_mask:0xf bank_mask:0xf
	s_waitcnt lgkmcnt(0)
	v_add_f32_e32 v44, v44, v45
	s_nop 1
	v_mov_b32_dpp v45, v44 row_ror:4 row_mask:0xf bank_mask:0xf
	s_waitcnt lgkmcnt(0)
	v_add_f32_e32 v0, v0, v1
	v_fmac_f32_e32 v35, 0xbb800000, v0
	v_fmac_f32_e32 v34, 0xbb800000, v0
	v_fmac_f32_e32 v33, 0xbb800000, v0
	v_fmac_f32_e32 v32, 0xbb800000, v0
	global_load_dwordx4 v[0:3], v[6:7], off
	s_waitcnt lgkmcnt(0)
	v_add_f32_e32 v44, v44, v45
	s_nop 1
	v_mov_b32_dpp v45, v44 quad_perm:[2,3,0,1] row_mask:0xf bank_mask:0xf
	v_pk_mul_f32 v[38:39], v[34:35], v[34:35]
	v_pk_mul_f32 v[36:37], v[32:33], v[32:33]
	v_mov_b32_e32 v49, v38
	s_waitcnt lgkmcnt(0)
	v_add_f32_e32 v44, v44, v45
	s_nop 1
	v_mov_b32_dpp v45, v44 quad_perm:[1,0,3,2] row_mask:0xf bank_mask:0xf
	s_waitcnt lgkmcnt(0)
	v_add_f32_e32 v44, v44, v45
	v_fmac_f32_e32 v29, 0xbb800000, v44
	v_fmac_f32_e32 v28, 0xbb800000, v44
	v_fmac_f32_e32 v31, 0xbb800000, v44
	v_fmac_f32_e32 v30, 0xbb800000, v44
	v_pk_mul_f32 v[46:47], v[28:29], v[28:29]
	v_pk_mul_f32 v[44:45], v[30:31], v[30:31]
	v_mov_b32_e32 v48, v46
	v_mov_b32_e32 v38, v47
	v_pk_add_f32 v[38:39], v[48:49], v[38:39]
	v_mov_b32_e32 v46, v44
	v_mov_b32_e32 v47, v36
	v_pk_add_f32 v[38:39], v[46:47], v[38:39]
	v_mov_b32_e32 v36, v45
	v_pk_add_f32 v[36:37], v[36:37], v[38:39]
	v_mov_b32_e32 v39, v37
	s_nop 1
	v_permlane32_swap_b32_e32 v39, v37
	v_mov_b32_e32 v38, v36
	s_nop 1
	v_permlane32_swap_b32_e32 v38, v36
	s_waitcnt lgkmcnt(0)
	v_pk_add_f32 v[36:37], v[36:37], v[38:39]
	v_mov_b32_e32 v39, v37
	s_nop 1
	v_permlane16_swap_b32_e32 v39, v37
	v_mov_b32_e32 v38, v36
	s_nop 1
	v_permlane16_swap_b32_e32 v38, v36
	s_waitcnt lgkmcnt(0)
	v_pk_add_f32 v[36:37], v[36:37], v[38:39]
	s_nop 1
	v_mov_b32_dpp v39, v37 row_ror:8 row_mask:0xf bank_mask:0xf
	s_nop 1
	v_mov_b32_dpp v38, v36 row_ror:8 row_mask:0xf bank_mask:0xf
	s_waitcnt lgkmcnt(0)
; __device__ __forceinline__ u32x2 pack4(f32x4 v) { u32x2 r; r[0] = cvt_pk(v[0], v[1]); r[1] = cvt_pk(v[2], v[3]); return r; }
; __device__ __forceinline__ f32x4 unpack4(u32x2 u) { f32x4 r; r[0] = bflo(u[0]); r[1] = bfhi(u[0]); r[2] = bflo(u[1]); r[3] = bfhi(u[1]); return r; }
; __device__ __forceinline__ void phase_retpost(const Params& p) {
;     ...
;     for (int q = 0; q < 8; ++q) {
;       const int pr = pr0 + q, r = pr >> 3, h = pr & 7;
;       const f32x4 x = unpack4(xr[q]);
;       const float mean = wave_sum(x[0] + x[1] + x[2] + x[3]) * (1.0f / 256.0f);
;       const f32x4 d = x - mean;
;       const float var = wave_sum(d[0] * d[0] + d[1] * d[1] + d[2] * d[2] + d[3] * d[3]) * (1.0f / 256.0f);
;       const float rstd = rsqrtf(var + LN_EPS);
;       const f32x4 gn = *(const f32x4*)(p.in[12] + h * 256 + 4 * lane);
;       const f32x4 sg = unpack4(sr[q]);
;       *(u32x2*)(ACAT + (size_t)r * 4096 + 1024 + h * 256 + 4 * lane) = pack4(d * rstd * gn * sg);
	v_pk_add_f32 v[36:37], v[36:37], v[38:39]
	s_nop 1
	v_mov_b32_dpp v39, v37 row_ror:4 row_mask:0xf bank_mask:0xf
	s_nop 1
	v_mov_b32_dpp v38, v36 row_ror:4 row_mask:0xf bank_mask:0xf
	s_waitcnt lgkmcnt(0)
	v_pk_add_f32 v[36:37], v[36:37], v[38:39]
	s_nop 1
	v_mov_b32_dpp v39, v37 quad_perm:[2,3,0,1] row_mask:0xf bank_mask:0xf
	s_nop 1
	v_mov_b32_dpp v38, v36 quad_perm:[2,3,0,1] row_mask:0xf bank_mask:0xf
	s_waitcnt lgkmcnt(0)
	v_pk_add_f32 v[36:37], v[36:37], v[38:39]
	s_nop 1
	v_mov_b32_dpp v39, v37 quad_perm:[1,0,3,2] row_mask:0xf bank_mask:0xf
	s_nop 1
	v_mov_b32_dpp v38, v36 quad_perm:[1,0,3,2] row_mask:0xf bank_mask:0xf
	s_waitcnt lgkmcnt(0)
	v_pk_add_f32 v[36:37], v[36:37], v[38:39]
	s_nop 0
	v_pk_fma_f32 v[36:37], v[36:37], s[30:31], v[24:25] op_sel_hi:[1,0,0]
	s_nop 0
	v_mul_f32_e32 v38, 0x4b800000, v37
	v_cmp_gt_f32_e64 s[36:37], s66, v37
	v_cmp_gt_f32_e32 vcc, s66, v36
	s_nop 0
	v_cndmask_b32_e64 v37, v37, v38, s[36:37]
	v_rsq_f32_e32 v37, v37
	s_nop 0
	v_mul_f32_e32 v38, 0x45800000, v37
	v_cndmask_b32_e64 v38, v37, v38, s[36:37]
	v_pk_mul_f32 v[32:33], v[32:33], v[38:39] op_sel_hi:[1,0]
	v_pk_mul_f32 v[34:35], v[34:35], v[38:39] op_sel_hi:[1,0]
	s_waitcnt vmcnt(0)
	v_pk_mul_f32 v[2:3], v[2:3], v[32:33]
	v_pk_mul_f32 v[0:1], v[0:1], v[34:35]
	v_pk_mul_f32 v[2:3], v[2:3], v[42:43]
	v_pk_mul_f32 v[0:1], v[0:1], v[40:41]
	v_lshlrev_b32_e32 v34, 16, v26
	v_cvt_pk_bf16_f32 v0, v0, v1
	v_cvt_pk_bf16_f32 v1, v2, v3
	global_store_dwordx2 v[16:17], v[0:1], off offset:2048
	v_mul_f32_e32 v0, 0x4b800000, v36
	v_cndmask_b32_e32 v0, v36, v0, vcc
	v_rsq_f32_e32 v0, v0
	v_and_b32_e32 v35, 0xffff0000, v26
	v_lshlrev_b32_e32 v26, 16, v27
	v_and_b32_e32 v27, 0xffff0000, v27
	v_mul_f32_e32 v1, 0x45800000, v0
	v_cndmask_b32_e32 v32, v0, v1, vcc
	global_load_dwordx4 v[0:3], v[8:9], off
	v_pk_mul_f32 v[30:31], v[30:31], v[32:33] op_sel_hi:[1,0]
	v_pk_mul_f32 v[28:29], v[28:29], v[32:33] op_sel_hi:[1,0]
	v_lshlrev_b32_e32 v32, 16, v20
	v_and_b32_e32 v33, 0xffff0000, v20
	v_lshlrev_b32_e32 v20, 16, v18
	s_waitcnt vmcnt(0)
	v_pk_mul_f32 v[0:1], v[0:1], v[28:29]
	v_pk_mul_f32 v[2:3], v[2:3], v[30:31]
	v_pk_mul_f32 v[0:1], v[0:1], v[34:35]
	v_pk_mul_f32 v[2:3], v[2:3], v[26:27]
	v_cvt_pk_bf16_f32 v0, v0, v1
	v_cvt_pk_bf16_f32 v1, v2, v3
	v_lshlrev_b32_e32 v26, 16, v22
	v_and_b32_e32 v27, 0xffff0000, v22
	global_store_dwordx2 v[16:17], v[0:1], off offset:2560
	v_lshlrev_b32_e32 v22, 16, v23
	v_add_f32_e32 v0, v26, v27
	v_and_b32_e32 v23, 0xffff0000, v23
	v_add_f32_e32 v0, v0, v22
	v_add_f32_e32 v0, v0, v23
	v_mov_b32_e32 v1, v0
	s_nop 1
	v_permlane32_swap_b32_e32 v1, v0
	v_lshlrev_b32_e32 v34, 16, v21
	v_and_b32_e32 v35, 0xffff0000, v21
	v_and_b32_e32 v21, 0xffff0000, v18
	v_lshlrev_b32_e32 v18, 16, v19
	s_waitcnt lgkmcnt(0)
	v_add_f32_e32 v0, v0, v1
	v_mov_b32_e32 v1, v0
	s_nop 1
	v_permlane16_swap_b32_e32 v1, v0
	v_add_f32_e32 v36, v20, v21
	v_and_b32_e32 v19, 0xffff0000, v19
	v_add_f32_e32 v36, v36, v18
	v_add_f32_e32 v36, v36, v19
	s_waitcnt lgkmcnt(0)
	v_add_f32_e32 v0, v0, v1
	s_nop 1
	v_mov_b32_dpp v1, v0 row_ror:8 row_mask:0xf bank_mask:0xf
	v_mov_b32_e32 v37, v36
	s_nop 1
	v_permlane32_swap_b32_e32 v37, v36
	s_waitcnt lgkmcnt(0)
	v_add_f32_e32 v0, v0, v1
	s_nop 1
	v_mov_b32_dpp v1, v0 row_ror:4 row_mask:0xf bank_mask:0xf
	s_waitcnt lgkmcnt(0)
	v_add_f32_e32 v36, v36, v37
	v_mov_b32_e32 v37, v36
	s_nop 1
	v_permlane16_swap_b32_e32 v37, v36
	s_waitcnt lgkmcnt(0)
	v_add_f32_e32 v0, v0, v1
	s_nop 1
	v_mov_b32_dpp v1, v0 quad_perm:[2,3,0,1] row_mask:0xf bank_mask:0xf
	s_waitcnt lgkmcnt(0)
	v_add_f32_e32 v36, v36, v37
	s_nop 1
	v_mov_b32_dpp v37, v36 row_ror:8 row_mask:0xf bank_mask:0xf
	s_waitcnt lgkmcnt(0)
	v_add_f32_e32 v0, v0, v1
	s_nop 1
	v_mov_b32_dpp v1, v0 quad_perm:[1,0,3,2] row_mask:0xf bank_mask:0xf
	s_waitcnt lgkmcnt(0)
	v_add_f32_e32 v36, v36, v37
	s_nop 1
	v_mov_b32_dpp v37, v36 row_ror:4 row_mask:0xf bank_mask:0xf
	s_waitcnt lgkmcnt(0)
; __device__ __forceinline__ u32x2 pack4(f32x4 v) { u32x2 r; r[0] = cvt_pk(v[0], v[1]); r[1] = cvt_pk(v[2], v[3]); return r; }
; __device__ __forceinline__ f32x4 unpack4(u32x2 u) { f32x4 r; r[0] = bflo(u[0]); r[1] = bfhi(u[0]); r[2] = bflo(u[1]); r[3] = bfhi(u[1]); return r; }
; __device__ __forceinline__ void phase_retpost(const Params& p) {
;     ...
;     for (int q = 0; q < 8; ++q) {
;       const int pr = pr0 + q, r = pr >> 3, h = pr & 7;
;       const f32x4 x = unpack4(xr[q]);
;       const float mean = wave_sum(x[0] + x[1] + x[2] + x[3]) * (1.0f / 256.0f);
;       const f32x4 d = x - mean;
;       const float var = wave_sum(d[0] * d[0] + d[1] * d[1] + d[2] * d[2] + d[3] * d[3]) * (1.0f / 256.0f);
;       const float rstd = rsqrtf(var + LN_EPS);
;       const f32x4 gn = *(const f32x4*)(p.in[12] + h * 256 + 4 * lane);
;       const f32x4 sg = unpack4(sr[q]);
;       *(u32x2*)(ACAT + (size_t)r * 4096 + 1024 + h * 256 + 4 * lane) = pack4(d * rstd * gn * sg);
	v_add_f32_e32 v0, v0, v1
	v_fmac_f32_e32 v27, 0xbb800000, v0
	v_fmac_f32_e32 v26, 0xbb800000, v0
	v_fmac_f32_e32 v23, 0xbb800000, v0
	v_fmac_f32_e32 v22, 0xbb800000, v0
	global_load_dwordx4 v[0:3], v[10:11], off
	s_waitcnt lgkmcnt(0)
	v_add_f32_e32 v36, v36, v37
	s_nop 1
	v_mov_b32_dpp v37, v36 quad_perm:[2,3,0,1] row_mask:0xf bank_mask:0xf
	v_pk_mul_f32 v[30:31], v[26:27], v[26:27]
	v_pk_mul_f32 v[28:29], v[22:23], v[22:23]
	v_mov_b32_e32 v41, v30
	s_waitcnt lgkmcnt(0)
	v_add_f32_e32 v36, v36, v37
	s_nop 1
	v_mov_b32_dpp v37, v36 quad_perm:[1,0,3,2] row_mask:0xf bank_mask:0xf
	s_waitcnt lgkmcnt(0)
	v_add_f32_e32 v36, v36, v37
	v_fmac_f32_e32 v21, 0xbb800000, v36
	v_fmac_f32_e32 v20, 0xbb800000, v36
	v_fmac_f32_e32 v19, 0xbb800000, v36
	v_fmac_f32_e32 v18, 0xbb800000, v36
	v_pk_mul_f32 v[38:39], v[20:21], v[20:21]
	v_pk_mul_f32 v[36:37], v[18:19], v[18:19]
	v_mov_b32_e32 v40, v38
	v_mov_b32_e32 v30, v39
	v_pk_add_f32 v[30:31], v[40:41], v[30:31]
	v_mov_b32_e32 v38, v36
	v_mov_b32_e32 v39, v28
	v_pk_add_f32 v[30:31], v[38:39], v[30:31]
	v_mov_b32_e32 v28, v37
	v_pk_add_f32 v[28:29], v[28:29], v[30:31]
	v_mov_b32_e32 v31, v29
	s_nop 1
	v_permlane32_swap_b32_e32 v31, v29
	v_mov_b32_e32 v30, v28
	s_nop 1
	v_permlane32_swap_b32_e32 v30, v28
	s_waitcnt lgkmcnt(0)
	v_pk_add_f32 v[28:29], v[28:29], v[30:31]
	v_mov_b32_e32 v31, v29
	s_nop 1
	v_permlane16_swap_b32_e32 v31, v29
	v_mov_b32_e32 v30, v28
	s_nop 1
	v_permlane16_swap_b32_e32 v30, v28
	s_waitcnt lgkmcnt(0)
	v_pk_add_f32 v[28:29], v[28:29], v[30:31]
	s_nop 1
	v_mov_b32_dpp v31, v29 row_ror:8 row_mask:0xf bank_mask:0xf
	s_nop 1
	v_mov_b32_dpp v30, v28 row_ror:8 row_mask:0xf bank_mask:0xf
	s_waitcnt lgkmcnt(0)
	v_pk_add_f32 v[28:29], v[28:29], v[30:31]
	s_nop 1
	v_mov_b32_dpp v31, v29 row_ror:4 row_mask:0xf bank_mask:0xf
	s_nop 1
	v_mov_b32_dpp v30, v28 row_ror:4 row_mask:0xf bank_mask:0xf
	s_waitcnt lgkmcnt(0)
	v_pk_add_f32 v[28:29], v[28:29], v[30:31]
	s_nop 1
	v_mov_b32_dpp v31, v29 quad_perm:[2,3,0,1] row_mask:0xf bank_mask:0xf
	s_nop 1
	v_mov_b32_dpp v30, v28 quad_perm:[2,3,0,1] row_mask:0xf bank_mask:0xf
	s_waitcnt lgkmcnt(0)
	v_pk_add_f32 v[28:29], v[28:29], v[30:31]
	s_nop 1
	v_mov_b32_dpp v31, v29 quad_perm:[1,0,3,2] row_mask:0xf bank_mask:0xf
	s_nop 1
	v_mov_b32_dpp v30, v28 quad_perm:[1,0,3,2] row_mask:0xf bank_mask:0xf
	s_waitcnt lgkmcnt(0)
	v_pk_add_f32 v[28:29], v[28:29], v[30:31]
	s_nop 0
	v_pk_fma_f32 v[24:25], v[28:29], s[30:31], v[24:25] op_sel_hi:[1,0,0]
	s_nop 0
	v_mul_f32_e32 v28, 0x4b800000, v25
	v_cmp_gt_f32_e64 s[36:37], s66, v25
	v_cmp_gt_f32_e32 vcc, s66, v24
	s_nop 0
	v_cndmask_b32_e64 v25, v25, v28, s[36:37]
	v_rsq_f32_e32 v25, v25
	s_nop 0
	v_mul_f32_e32 v28, 0x45800000, v25
	v_cndmask_b32_e64 v28, v25, v28, s[36:37]
	v_pk_mul_f32 v[22:23], v[22:23], v[28:29] op_sel_hi:[1,0]
	v_pk_mul_f32 v[26:27], v[26:27], v[28:29] op_sel_hi:[1,0]
	s_waitcnt vmcnt(0)
	v_pk_mul_f32 v[2:3], v[2:3], v[22:23]
	v_pk_mul_f32 v[0:1], v[0:1], v[26:27]
	v_pk_mul_f32 v[2:3], v[2:3], v[34:35]
	v_pk_mul_f32 v[0:1], v[0:1], v[32:33]
	v_and_b32_e32 v25, 0xffff0000, v14
	v_cvt_pk_bf16_f32 v0, v0, v1
	v_cvt_pk_bf16_f32 v1, v2, v3
	global_store_dwordx2 v[16:17], v[0:1], off offset:3072
	v_mul_f32_e32 v0, 0x4b800000, v24
	v_cndmask_b32_e32 v0, v24, v0, vcc
	v_rsq_f32_e32 v0, v0
	v_lshlrev_b32_e32 v24, 16, v14
	v_lshlrev_b32_e32 v14, 16, v15
	v_and_b32_e32 v15, 0xffff0000, v15
	v_mul_f32_e32 v1, 0x45800000, v0
	v_cndmask_b32_e32 v22, v0, v1, vcc
	global_load_dwordx4 v[0:3], v[12:13], off
	v_pk_mul_f32 v[18:19], v[18:19], v[22:23] op_sel_hi:[1,0]
	v_pk_mul_f32 v[20:21], v[20:21], v[22:23] op_sel_hi:[1,0]
	v_cmp_lt_i32_e32 vcc, s29, v62
	s_or_b64 s[42:43], vcc, s[42:43]
	s_waitcnt vmcnt(0)
	v_pk_mul_f32 v[0:1], v[0:1], v[20:21]
	v_pk_mul_f32 v[2:3], v[2:3], v[18:19]
	v_pk_mul_f32 v[0:1], v[0:1], v[24:25]
	v_pk_mul_f32 v[2:3], v[2:3], v[14:15]
	v_cvt_pk_bf16_f32 v0, v0, v1
	v_cvt_pk_bf16_f32 v1, v2, v3
	global_store_dwordx2 v[16:17], v[0:1], off offset:3584
	s_andn2_b64 exec, exec, s[42:43]
	s_cbranch_execnz .LBB0_174

; __device__ __forceinline__ void ln_finish_row(int r, int lane, f32x4 (&x)[8], float* dstf, bf16_t* dstb, const float* g, const float* bta) {
;   float sm = 0.f;
; #pragma unroll
;   for (int k = 0; k < 8; ++k) sm += x[k][0] + x[k][1] + x[k][2] + x[k][3];
;   const float mean = wave_sum(sm) * (1.0f / 2048.0f);
;   float q = 0.f;
; #pragma unroll
;   for (int k = 0; k < 8; ++k) { x[k] = x[k] - mean; q += x[k][0] * x[k][0] + x[k][1] * x[k][1] + x[k][2] * x[k][2] + x[k][3] * x[k][3]; }
;   const float rstd = rsqrtf(wave_sum(q) * (1.0f / 2048.0f) + LN_EPS);
.LBB0_1561:
	s_or_b64 exec, exec, s[42:43]
	s_waitcnt vmcnt(0)
	v_add_f32_e32 v64, v20, v21
	v_add_f32_e32 v64, v22, v64
	v_add_f32_e32 v67, v28, v29
	v_add_f32_e32 v64, v23, v64
	v_add_f32_e32 v67, v30, v67
	v_add_f32_e32 v64, 0, v64
	v_add_f32_e32 v67, v31, v67
	v_add_f32_e32 v64, v64, v67
	v_add_f32_e32 v67, v36, v37
	v_add_f32_e32 v67, v38, v67
	v_add_f32_e32 v67, v39, v67
	v_add_f32_e32 v64, v64, v67
	v_add_f32_e32 v67, v44, v45
	v_mov_b32_e32 v112, v48
	v_mov_b32_e32 v113, v52
	v_mov_b32_e32 v114, v49
	v_mov_b32_e32 v115, v53
	v_add_f32_e32 v67, v46, v67
	v_pk_add_f32 v[112:113], v[112:113], v[114:115]
	v_mov_b32_e32 v114, v50
	v_mov_b32_e32 v115, v54
	v_add_f32_e32 v67, v47, v67
	v_pk_add_f32 v[112:113], v[114:115], v[112:113]
	v_mov_b32_e32 v114, v51
	v_mov_b32_e32 v115, v55
	v_add_f32_e32 v64, v64, v67
	v_pk_add_f32 v[112:113], v[114:115], v[112:113]
	v_mov_b32_e32 v114, v57
	v_add_f32_e32 v64, v64, v112
	v_add_f32_e32 v64, v64, v113
	v_mov_b32_e32 v112, v56
	v_mov_b32_e32 v113, v60
	v_mov_b32_e32 v115, v61
	v_pk_add_f32 v[112:113], v[112:113], v[114:115]
	v_mov_b32_e32 v114, v58
	v_mov_b32_e32 v115, v62
	v_pk_add_f32 v[112:113], v[114:115], v[112:113]
	v_mov_b32_e32 v114, v59
	v_mov_b32_e32 v115, v63
	v_pk_add_f32 v[112:113], v[114:115], v[112:113]
	global_load_dwordx4 v[128:131], v[70:71], off
	global_load_dwordx4 v[132:135], v[72:73], off
	v_add_f32_e32 v64, v64, v112
	v_add_f32_e32 v64, v64, v113
	v_mov_b32_e32 v67, v64
	s_nop 1
	v_permlane32_swap_b32_e32 v67, v64
	s_mov_b32 s29, 0x800000
	s_waitcnt lgkmcnt(0)
	v_add_f32_e32 v64, v64, v67
	v_mov_b32_e32 v67, v64
	s_nop 1
	v_permlane16_swap_b32_e32 v67, v64
	s_waitcnt lgkmcnt(0)
	v_add_f32_e32 v64, v64, v67
	s_nop 1
	v_mov_b32_dpp v67, v64 row_ror:8 row_mask:0xf bank_mask:0xf
	s_waitcnt lgkmcnt(0)
	v_add_f32_e32 v64, v64, v67
	s_nop 1
	v_mov_b32_dpp v67, v64 row_ror:4 row_mask:0xf bank_mask:0xf
	s_waitcnt lgkmcnt(0)
	v_add_f32_e32 v64, v64, v67
	s_nop 1
	v_mov_b32_dpp v67, v64 quad_perm:[2,3,0,1] row_mask:0xf bank_mask:0xf
	s_waitcnt lgkmcnt(0)
	v_add_f32_e32 v64, v64, v67
	s_nop 1
	v_mov_b32_dpp v67, v64 quad_perm:[1,0,3,2] row_mask:0xf bank_mask:0xf
	s_waitcnt lgkmcnt(0)
	v_add_f32_e32 v64, v64, v67
	v_fmac_f32_e32 v21, 0xba000000, v64
	v_fmac_f32_e32 v29, 0xba000000, v64
	v_fmamk_f32 v119, v64, 0xba000000, v23
	v_fmamk_f32 v118, v64, 0xba000000, v22
	v_fmamk_f32 v20, v64, 0xba000000, v20
	v_mul_f32_e32 v22, v21, v21
	v_fmamk_f32 v28, v64, 0xba000000, v28
	v_mul_f32_e32 v23, v29, v29
	v_fmac_f32_e32 v22, v20, v20
	v_fmamk_f32 v116, v64, 0xba000000, v30
	v_fmac_f32_e32 v23, v28, v28
	v_fmac_f32_e32 v22, v118, v118
	v_fmamk_f32 v117, v64, 0xba000000, v31
	v_fmac_f32_e32 v23, v116, v116
	v_fmac_f32_e32 v22, v119, v119
	v_fmac_f32_e32 v23, v117, v117
	v_fmac_f32_e32 v37, 0xba000000, v64
	v_add_f32_e32 v22, v22, v23
	v_fmamk_f32 v36, v64, 0xba000000, v36
	v_mul_f32_e32 v23, v37, v37
	v_fmamk_f32 v114, v64, 0xba000000, v38
	v_fmac_f32_e32 v23, v36, v36
	v_fmamk_f32 v115, v64, 0xba000000, v39
	v_fmac_f32_e32 v23, v114, v114
	v_fmac_f32_e32 v23, v115, v115
	v_fmac_f32_e32 v45, 0xba000000, v64
	v_add_f32_e32 v22, v23, v22
	v_fmamk_f32 v44, v64, 0xba000000, v44
	v_mul_f32_e32 v23, v45, v45
	v_fmamk_f32 v112, v64, 0xba000000, v46
	v_fmac_f32_e32 v23, v44, v44
	v_fmamk_f32 v113, v64, 0xba000000, v47
	v_fmac_f32_e32 v23, v112, v112
	v_fmamk_f32 v49, v64, 0xba000000, v49
	v_fmamk_f32 v53, v64, 0xba000000, v53
	v_fmac_f32_e32 v23, v113, v113
	v_fmac_f32_e32 v48, 0xba000000, v64
	v_fmac_f32_e32 v52, 0xba000000, v64
	v_mov_b32_e32 v38, v53
	v_mov_b32_e32 v39, v49
	v_add_f32_e32 v46, v23, v22
	v_fmamk_f32 v50, v64, 0xba000000, v50
	v_fmamk_f32 v30, v64, 0xba000000, v54
	v_mov_b32_e32 v22, v52
	v_mov_b32_e32 v23, v48
	v_pk_mul_f32 v[38:39], v[38:39], v[38:39]
	v_fmamk_f32 v51, v64, 0xba000000, v51
	v_fmamk_f32 v31, v64, 0xba000000, v55
	v_pk_fma_f32 v[22:23], v[22:23], v[22:23], v[38:39]
	v_mov_b32_e32 v38, v30
	v_mov_b32_e32 v39, v50
	v_pk_fma_f32 v[22:23], v[38:39], v[38:39], v[22:23]
	v_mov_b32_e32 v38, v31
	v_mov_b32_e32 v39, v51
	v_pk_fma_f32 v[22:23], v[38:39], v[38:39], v[22:23]
	v_fmamk_f32 v57, v64, 0xba000000, v57
	v_fmamk_f32 v61, v64, 0xba000000, v61
	v_add_f32_e32 v23, v23, v46
	v_fmac_f32_e32 v56, 0xba000000, v64
	v_fmac_f32_e32 v60, 0xba000000, v64
	v_mov_b32_e32 v54, v61
	v_mov_b32_e32 v55, v57
	v_add_f32_e32 v67, v22, v23
	v_fmamk_f32 v38, v64, 0xba000000, v58
	v_fmamk_f32 v22, v64, 0xba000000, v62
	v_mov_b32_e32 v46, v60
	v_mov_b32_e32 v47, v56
	v_pk_mul_f32 v[54:55], v[54:55], v[54:55]
	v_fmamk_f32 v39, v64, 0xba000000, v59
	v_fmamk_f32 v23, v64, 0xba000000, v63
	v_pk_fma_f32 v[46:47], v[46:47], v[46:47], v[54:55]
	v_mov_b32_e32 v54, v22
	v_mov_b32_e32 v55, v38
	v_pk_fma_f32 v[46:47], v[54:55], v[54:55], v[46:47]
	v_mov_b32_e32 v54, v23
	v_mov_b32_e32 v55, v39
	v_pk_fma_f32 v[46:47], v[54:55], v[54:55], v[46:47]
	s_nop 0
	v_add_f32_e32 v47, v47, v67
	v_add_f32_e32 v46, v46, v47
	v_mov_b32_e32 v47, v46
	s_nop 1
	v_permlane32_swap_b32_e32 v47, v46
	s_waitcnt lgkmcnt(0)
	v_add_f32_e32 v46, v46, v47
	v_mov_b32_e32 v47, v46
	s_nop 1
	v_permlane16_swap_b32_e32 v47, v46
	s_waitcnt lgkmcnt(0)
	v_add_f32_e32 v46, v46, v47
	s_nop 1
	v_mov_b32_dpp v47, v46 row_ror:8 row_mask:0xf bank_mask:0xf
	s_waitcnt lgkmcnt(0)
	v_add_f32_e32 v46, v46, v47
	s_nop 1
	v_mov_b32_dpp v47, v46 row_ror:4 row_mask:0xf bank_mask:0xf
	s_waitcnt lgkmcnt(0)
	v_add_f32_e32 v46, v46, v47
	s_nop 1
	v_mov_b32_dpp v47, v46 quad_perm:[2,3,0,1] row_mask:0xf bank_mask:0xf
	s_waitcnt lgkmcnt(0)
	v_add_f32_e32 v46, v46, v47
	s_nop 1
	v_mov_b32_dpp v47, v46 quad_perm:[1,0,3,2] row_mask:0xf bank_mask:0xf
	s_waitcnt lgkmcnt(0)
; __device__ __forceinline__ u32x2 pack4(f32x4 v) { u32x2 r; r[0] = cvt_pk(v[0], v[1]); r[1] = cvt_pk(v[2], v[3]); return r; }
; __device__ __forceinline__ void ln_finish_row(int r, int lane, f32x4 (&x)[8], float* dstf, bf16_t* dstb, const float* g, const float* bta) {
;   float sm = 0.f;
; #pragma unroll
;   for (int k = 0; k < 8; ++k) sm += x[k][0] + x[k][1] + x[k][2] + x[k][3];
;   const float mean = wave_sum(sm) * (1.0f / 2048.0f);
;     ...
;   const float rstd = rsqrtf(wave_sum(q) * (1.0f / 2048.0f) + LN_EPS);
; #pragma unroll
;   for (int k = 0; k < 8; ++k) {
;     const int col = 256 * k + 4 * lane;
;     const f32x4 gg = *(const f32x4*)(g + col), bb = *(const f32x4*)(bta + col);
;     const f32x4 y = x[k] * rstd * gg + bb;
;     *(f32x4*)(dstf + (size_t)r * 2048 + col) = y;
;     if (dstb) *(u32x2*)(dstb + (size_t)r * 2048 + col) = pack4(y);
;   }
	v_add_f32_e32 v46, v46, v47
	v_fmamk_f32 v46, v46, 0x3a000000, v228
	v_cmp_gt_f32_e32 vcc, s29, v46
	v_mul_f32_e32 v47, 0x4b800000, v46
	s_movk_i32 s29, 0x1000
	v_cndmask_b32_e32 v46, v46, v47, vcc
	v_rsq_f32_e32 v46, v46
	s_nop 0
	v_mul_f32_e32 v47, 0x45800000, v46
	v_cndmask_b32_e32 v46, v46, v47, vcc
	v_pk_mul_f32 v[20:21], v[20:21], v[46:47] op_sel_hi:[1,0]
	v_pk_mul_f32 v[54:55], v[118:119], v[46:47] op_sel_hi:[1,0]
	s_waitcnt vmcnt(0)
	v_pk_fma_f32 v[128:129], v[128:129], v[20:21], v[132:133]
	v_pk_fma_f32 v[130:131], v[130:131], v[54:55], v[134:135]
	v_lshl_add_u64 v[20:21], v[98:99], 0, v[94:95]
	global_store_dwordx4 v[20:21], v[128:131], off
	global_load_dwordx4 v[128:131], v[70:71], off offset:1024
	s_nop 0
	global_load_dwordx4 v[132:135], v[72:73], off offset:1024
	v_pk_mul_f32 v[54:55], v[116:117], v[46:47] op_sel_hi:[1,0]
	v_pk_mul_f32 v[28:29], v[28:29], v[46:47] op_sel_hi:[1,0]
	v_pk_mul_f32 v[36:37], v[36:37], v[46:47] op_sel_hi:[1,0]
	v_pk_mul_f32 v[22:23], v[22:23], v[46:47] op_sel_hi:[1,0]
	s_waitcnt vmcnt(0)
	v_pk_fma_f32 v[116:117], v[128:129], v[28:29], v[132:133]
	v_pk_fma_f32 v[118:119], v[130:131], v[54:55], v[134:135]
	global_store_dwordx4 v[20:21], v[116:119], off offset:1024
	global_load_dwordx4 v[116:119], v[70:71], off offset:2048
	s_nop 0
	global_load_dwordx4 v[128:131], v[72:73], off offset:2048
	v_pk_mul_f32 v[28:29], v[114:115], v[46:47] op_sel_hi:[1,0]
	s_waitcnt vmcnt(0)
	v_pk_fma_f32 v[114:115], v[116:117], v[36:37], v[128:129]
	v_pk_fma_f32 v[116:117], v[118:119], v[28:29], v[130:131]
	global_store_dwordx4 v[20:21], v[114:117], off offset:2048
	global_load_dwordx4 v[114:117], v[70:71], off offset:3072
	s_nop 0
	global_load_dwordx4 v[128:131], v[72:73], off offset:3072
	v_pk_mul_f32 v[28:29], v[112:113], v[46:47] op_sel_hi:[1,0]
	v_pk_mul_f32 v[36:37], v[44:45], v[46:47] op_sel_hi:[1,0]
	v_add_co_u32_e32 v44, vcc, s29, v20
	s_waitcnt vmcnt(0)
	v_pk_fma_f32 v[112:113], v[114:115], v[36:37], v[128:129]
	v_pk_fma_f32 v[114:115], v[116:117], v[28:29], v[130:131]
	global_store_dwordx4 v[20:21], v[112:115], off offset:3072
	global_load_dwordx4 v[112:115], v[74:75], off
	s_nop 0
	global_load_dwordx4 v[116:119], v[76:77], off
	v_pk_mul_f32 v[28:29], v[50:51], v[46:47] op_sel_hi:[1,0]
	v_pk_mul_f32 v[36:37], v[48:49], v[46:47] op_sel_hi:[1,0]
	v_addc_co_u32_e32 v45, vcc, 0, v21, vcc
	v_pk_mul_f32 v[20:21], v[30:31], v[46:47] op_sel_hi:[1,0]
	s_waitcnt vmcnt(0)
	v_pk_fma_f32 v[48:49], v[112:113], v[36:37], v[116:117]
	v_pk_fma_f32 v[50:51], v[114:115], v[28:29], v[118:119]
	global_store_dwordx4 v[44:45], v[48:51], off
	global_load_dwordx4 v[48:51], v[78:79], off
	s_nop 0
	global_load_dwordx4 v[112:115], v[80:81], off
	v_pk_mul_f32 v[28:29], v[52:53], v[46:47] op_sel_hi:[1,0]
	v_pk_mul_f32 v[36:37], v[56:57], v[46:47] op_sel_hi:[1,0]
	s_waitcnt vmcnt(0)
	v_pk_fma_f32 v[28:29], v[48:49], v[28:29], v[112:113]
	v_pk_fma_f32 v[30:31], v[50:51], v[20:21], v[114:115]
	global_store_dwordx4 v[44:45], v[28:31], off offset:1024
	global_load_dwordx4 v[28:31], v[82:83], off
	s_nop 0
	global_load_dwordx4 v[48:51], v[84:85], off
	v_pk_mul_f32 v[20:21], v[38:39], v[46:47] op_sel_hi:[1,0]
	s_waitcnt vmcnt(0)
	v_pk_fma_f32 v[28:29], v[28:29], v[36:37], v[48:49]
	v_pk_fma_f32 v[30:31], v[30:31], v[20:21], v[50:51]
	global_store_dwordx4 v[44:45], v[28:31], off offset:2048
	global_load_dwordx4 v[28:31], v[86:87], off
	s_nop 0
	global_load_dwordx4 v[36:39], v[88:89], off
	v_pk_mul_f32 v[20:21], v[60:61], v[46:47] op_sel_hi:[1,0]
	s_waitcnt vmcnt(0)
	v_pk_fma_f32 v[22:23], v[30:31], v[22:23], v[38:39]
	v_pk_fma_f32 v[20:21], v[28:29], v[20:21], v[36:37]
	global_store_dwordx4 v[44:45], v[20:23], off offset:3072
	s_and_saveexec_b64 s[42:43], s[36:37]
	s_cbranch_execz .LBB0_1494
	v_add_f32_e32 v20, v0, v1
	v_add_f32_e32 v20, v2, v20
	v_add_f32_e32 v21, v4, v5
	v_add_f32_e32 v20, v3, v20
	v_add_f32_e32 v21, v6, v21
	v_add_f32_e32 v20, 0, v20
	v_add_f32_e32 v21, v7, v21
	v_add_f32_e32 v20, v21, v20
	v_add_f32_e32 v21, v8, v9
	v_add_f32_e32 v21, v10, v21
	v_add_f32_e32 v21, v11, v21
	v_add_f32_e32 v20, v21, v20
	v_add_f32_e32 v21, v12, v13
	v_add_f32_e32 v21, v14, v21
	v_add_f32_e32 v21, v15, v21
	v_add_f32_e32 v28, v21, v20
	v_mov_b32_e32 v20, v24
	v_mov_b32_e32 v21, v16
	v_mov_b32_e32 v22, v25
	v_mov_b32_e32 v23, v17
	v_pk_add_f32 v[20:21], v[20:21], v[22:23]
	v_mov_b32_e32 v22, v26
	v_mov_b32_e32 v23, v18
	v_pk_add_f32 v[20:21], v[22:23], v[20:21]
	v_mov_b32_e32 v22, v27
	v_mov_b32_e32 v23, v19
	v_pk_add_f32 v[20:21], v[22:23], v[20:21]
	v_mov_b32_e32 v22, v41
	v_add_f32_e32 v21, v21, v28
	v_add_f32_e32 v28, v20, v21
	v_mov_b32_e32 v20, v40
	v_mov_b32_e32 v21, v32
	v_mov_b32_e32 v23, v33
	v_pk_add_f32 v[20:21], v[20:21], v[22:23]
	v_mov_b32_e32 v22, v42
	v_mov_b32_e32 v23, v34
	v_pk_add_f32 v[20:21], v[22:23], v[20:21]
	v_mov_b32_e32 v22, v43
	v_mov_b32_e32 v23, v35
	v_pk_add_f32 v[20:21], v[22:23], v[20:21]
	s_mov_b32 s29, 0x800000
	v_add_f32_e32 v21, v21, v28
	v_add_f32_e32 v20, v20, v21
	v_mov_b32_e32 v21, v20
	s_nop 1
	v_permlane32_swap_b32_e32 v21, v20
	v_ashrrev_i32_e32 v111, 31, v110
	v_mov_b32_e32 v101, v65
	v_mov_b32_e32 v103, v65
	v_mov_b32_e32 v105, v65
	s_waitcnt lgkmcnt(0)
	v_add_f32_e32 v20, v20, v21
	v_mov_b32_e32 v21, v20
	s_nop 1
	v_permlane16_swap_b32_e32 v21, v20
	v_mov_b32_e32 v107, v65
	v_mov_b32_e32 v109, v65
	s_waitcnt lgkmcnt(0)
	v_add_f32_e32 v20, v20, v21
	s_nop 1
	v_mov_b32_dpp v21, v20 row_ror:8 row_mask:0xf bank_mask:0xf
	s_waitcnt lgkmcnt(0)
	v_add_f32_e32 v20, v20, v21
	s_nop 1
	v_mov_b32_dpp v21, v20 row_ror:4 row_mask:0xf bank_mask:0xf
	s_waitcnt lgkmcnt(0)
; __device__ __forceinline__ void ln_finish_row(int r, int lane, f32x4 (&x)[8], float* dstf, bf16_t* dstb, const float* g, const float* bta) {
;   float sm = 0.f;
; #pragma unroll
;   for (int k = 0; k < 8; ++k) sm += x[k][0] + x[k][1] + x[k][2] + x[k][3];
;   const float mean = wave_sum(sm) * (1.0f / 2048.0f);
;   float q = 0.f;
; #pragma unroll
;   for (int k = 0; k < 8; ++k) { x[k] = x[k] - mean; q += x[k][0] * x[k][0] + x[k][1] * x[k][1] + x[k][2] * x[k][2] + x[k][3] * x[k][3]; }
;   const float rstd = rsqrtf(wave_sum(q) * (1.0f / 2048.0f) + LN_EPS);
	v_add_f32_e32 v20, v20, v21
	s_nop 1
	v_mov_b32_dpp v21, v20 quad_perm:[2,3,0,1] row_mask:0xf bank_mask:0xf
	s_waitcnt lgkmcnt(0)
	v_add_f32_e32 v20, v20, v21
	s_nop 1
	v_mov_b32_dpp v21, v20 quad_perm:[1,0,3,2] row_mask:0xf bank_mask:0xf
	s_waitcnt lgkmcnt(0)
	v_add_f32_e32 v44, v20, v21
	v_fmamk_f32 v1, v44, 0xba000000, v1
	v_fmamk_f32 v5, v44, 0xba000000, v5
	v_fmac_f32_e32 v0, 0xba000000, v44
	v_mul_f32_e32 v20, v1, v1
	v_fmac_f32_e32 v4, 0xba000000, v44
	v_mul_f32_e32 v21, v5, v5
	v_fmamk_f32 v2, v44, 0xba000000, v2
	v_fmac_f32_e32 v20, v0, v0
	v_fmamk_f32 v6, v44, 0xba000000, v6
	v_fmac_f32_e32 v21, v4, v4
	v_fmamk_f32 v3, v44, 0xba000000, v3
	v_fmac_f32_e32 v20, v2, v2
	v_fmamk_f32 v7, v44, 0xba000000, v7
	v_fmac_f32_e32 v21, v6, v6
	v_fmac_f32_e32 v20, v3, v3
	v_fmac_f32_e32 v21, v7, v7
	v_fmamk_f32 v9, v44, 0xba000000, v9
	v_add_f32_e32 v20, v20, v21
	v_fmac_f32_e32 v8, 0xba000000, v44
	v_mul_f32_e32 v21, v9, v9
	v_fmamk_f32 v10, v44, 0xba000000, v10
	v_fmac_f32_e32 v21, v8, v8
	v_fmamk_f32 v11, v44, 0xba000000, v11
	v_fmac_f32_e32 v21, v10, v10
	v_fmac_f32_e32 v21, v11, v11
	v_fmamk_f32 v13, v44, 0xba000000, v13
	v_add_f32_e32 v20, v21, v20
	v_fmac_f32_e32 v12, 0xba000000, v44
	v_mul_f32_e32 v21, v13, v13
	v_fmamk_f32 v14, v44, 0xba000000, v14
	v_fmac_f32_e32 v21, v12, v12
	v_fmamk_f32 v15, v44, 0xba000000, v15
	v_fmac_f32_e32 v21, v14, v14
	v_fmamk_f32 v17, v44, 0xba000000, v17
	v_fmamk_f32 v25, v44, 0xba000000, v25
	v_fmac_f32_e32 v21, v15, v15
	v_fmac_f32_e32 v16, 0xba000000, v44
	v_fmac_f32_e32 v24, 0xba000000, v44
	v_mov_b32_e32 v22, v25
	v_mov_b32_e32 v23, v17
	v_add_f32_e32 v45, v21, v20
	v_mov_b32_e32 v20, v24
	v_mov_b32_e32 v21, v16
	v_pk_mul_f32 v[22:23], v[22:23], v[22:23]
	v_fmamk_f32 v18, v44, 0xba000000, v18
	v_pk_fma_f32 v[36:37], v[20:21], v[20:21], v[22:23]
	global_load_dwordx4 v[20:23], v[70:71], off
	global_load_dwordx4 v[28:31], v[72:73], off
	v_fmamk_f32 v26, v44, 0xba000000, v26
	v_fmamk_f32 v19, v44, 0xba000000, v19
	v_fmamk_f32 v27, v44, 0xba000000, v27
	v_mov_b32_e32 v38, v26
	v_mov_b32_e32 v39, v18
	v_pk_fma_f32 v[36:37], v[38:39], v[38:39], v[36:37]
	v_mov_b32_e32 v38, v27
	v_mov_b32_e32 v39, v19
	v_pk_fma_f32 v[36:37], v[38:39], v[38:39], v[36:37]
	v_fmamk_f32 v33, v44, 0xba000000, v33
	v_fmamk_f32 v41, v44, 0xba000000, v41
	v_add_f32_e32 v37, v37, v45
	v_fmac_f32_e32 v32, 0xba000000, v44
	v_fmac_f32_e32 v40, 0xba000000, v44
	v_mov_b32_e32 v38, v41
	v_mov_b32_e32 v39, v33
	v_add_f32_e32 v45, v36, v37
	v_fmamk_f32 v34, v44, 0xba000000, v34
	v_fmamk_f32 v42, v44, 0xba000000, v42
	v_mov_b32_e32 v36, v40
	v_mov_b32_e32 v37, v32
	v_pk_mul_f32 v[38:39], v[38:39], v[38:39]
	v_fmamk_f32 v35, v44, 0xba000000, v35
	v_fmamk_f32 v43, v44, 0xba000000, v43
	v_pk_fma_f32 v[36:37], v[36:37], v[36:37], v[38:39]
	v_mov_b32_e32 v38, v42
	v_mov_b32_e32 v39, v34
	v_pk_fma_f32 v[36:37], v[38:39], v[38:39], v[36:37]
	v_mov_b32_e32 v38, v43
	v_mov_b32_e32 v39, v35
	v_pk_fma_f32 v[36:37], v[38:39], v[38:39], v[36:37]
	v_lshlrev_b64 v[38:39], 13, v[110:111]
	v_add_f32_e32 v37, v37, v45
	v_add_f32_e32 v36, v36, v37
	v_mov_b32_e32 v37, v36
	s_nop 1
	v_permlane32_swap_b32_e32 v37, v36
	v_lshl_add_u64 v[38:39], s[22:23], 0, v[38:39]
	s_waitcnt lgkmcnt(0)
	v_add_f32_e32 v36, v36, v37
	v_mov_b32_e32 v37, v36
	s_nop 1
	v_permlane16_swap_b32_e32 v37, v36
	s_waitcnt lgkmcnt(0)
	v_add_f32_e32 v36, v36, v37
	s_nop 1
	v_mov_b32_dpp v37, v36 row_ror:8 row_mask:0xf bank_mask:0xf
	s_waitcnt lgkmcnt(0)
	v_add_f32_e32 v36, v36, v37
	s_nop 1
	v_mov_b32_dpp v37, v36 row_ror:4 row_mask:0xf bank_mask:0xf
	s_waitcnt lgkmcnt(0)
	v_add_f32_e32 v36, v36, v37
	s_nop 1
	v_mov_b32_dpp v37, v36 quad_perm:[2,3,0,1] row_mask:0xf bank_mask:0xf
	s_waitcnt lgkmcnt(0)
; __device__ __forceinline__ u32x2 pack4(f32x4 v) { u32x2 r; r[0] = cvt_pk(v[0], v[1]); r[1] = cvt_pk(v[2], v[3]); return r; }
; __device__ __forceinline__ void ln_finish_row(int r, int lane, f32x4 (&x)[8], float* dstf, bf16_t* dstb, const float* g, const float* bta) {
;     ...
;   const float rstd = rsqrtf(wave_sum(q) * (1.0f / 2048.0f) + LN_EPS);
; #pragma unroll
;   for (int k = 0; k < 8; ++k) {
;     const int col = 256 * k + 4 * lane;
;     const f32x4 gg = *(const f32x4*)(g + col), bb = *(const f32x4*)(bta + col);
;     const f32x4 y = x[k] * rstd * gg + bb;
;     *(f32x4*)(dstf + (size_t)r * 2048 + col) = y;
;     if (dstb) *(u32x2*)(dstb + (size_t)r * 2048 + col) = pack4(y);
;   }
	v_add_f32_e32 v36, v36, v37
	s_nop 1
	v_mov_b32_dpp v37, v36 quad_perm:[1,0,3,2] row_mask:0xf bank_mask:0xf
	s_waitcnt lgkmcnt(0)
	v_add_f32_e32 v36, v36, v37
	v_fmamk_f32 v36, v36, 0x3a000000, v228
	v_mul_f32_e32 v37, 0x4b800000, v36
	v_cmp_gt_f32_e32 vcc, s29, v36
	s_nop 1
	v_cndmask_b32_e32 v36, v36, v37, vcc
	v_rsq_f32_e32 v36, v36
	s_nop 0
	v_mul_f32_e32 v37, 0x45800000, v36
	v_cndmask_b32_e32 v36, v36, v37, vcc
	v_pk_mul_f32 v[44:45], v[0:1], v[36:37] op_sel_hi:[1,0]
	v_pk_mul_f32 v[46:47], v[2:3], v[36:37] op_sel_hi:[1,0]
	s_waitcnt vmcnt(0)
	v_pk_fma_f32 v[20:21], v[20:21], v[44:45], v[28:29]
	v_pk_fma_f32 v[22:23], v[22:23], v[46:47], v[30:31]
	v_lshl_add_u64 v[44:45], v[38:39], 0, v[100:101]
	global_store_dwordx4 v[44:45], v[20:23], off
	global_load_dwordx4 v[20:23], v[70:71], off offset:1024
	s_nop 0
	global_load_dwordx4 v[28:31], v[72:73], off offset:1024
	v_pk_mul_f32 v[46:47], v[6:7], v[36:37] op_sel_hi:[1,0]
	v_pk_mul_f32 v[48:49], v[4:5], v[36:37] op_sel_hi:[1,0]
	s_waitcnt vmcnt(0)
	v_pk_fma_f32 v[22:23], v[22:23], v[46:47], v[30:31]
	v_pk_fma_f32 v[20:21], v[20:21], v[48:49], v[28:29]
	global_store_dwordx4 v[44:45], v[20:23], off offset:1024
	global_load_dwordx4 v[20:23], v[70:71], off offset:2048
	s_nop 0
	global_load_dwordx4 v[28:31], v[72:73], off offset:2048
	v_pk_mul_f32 v[46:47], v[10:11], v[36:37] op_sel_hi:[1,0]
	v_pk_mul_f32 v[48:49], v[8:9], v[36:37] op_sel_hi:[1,0]
	s_waitcnt vmcnt(0)
	v_pk_fma_f32 v[22:23], v[22:23], v[46:47], v[30:31]
	v_pk_fma_f32 v[20:21], v[20:21], v[48:49], v[28:29]
	global_store_dwordx4 v[44:45], v[20:23], off offset:2048
	global_load_dwordx4 v[20:23], v[70:71], off offset:3072
	s_nop 0
	global_load_dwordx4 v[28:31], v[72:73], off offset:3072
	v_pk_mul_f32 v[46:47], v[14:15], v[36:37] op_sel_hi:[1,0]
	v_pk_mul_f32 v[48:49], v[12:13], v[36:37] op_sel_hi:[1,0]
	s_waitcnt vmcnt(0)
	v_pk_fma_f32 v[22:23], v[22:23], v[46:47], v[30:31]
	v_pk_fma_f32 v[20:21], v[20:21], v[48:49], v[28:29]
	global_store_dwordx4 v[44:45], v[20:23], off offset:3072
	global_load_dwordx4 v[20:23], v[74:75], off
	s_nop 0
	global_load_dwordx4 v[28:31], v[76:77], off
	v_pk_mul_f32 v[46:47], v[18:19], v[36:37] op_sel_hi:[1,0]
	v_pk_mul_f32 v[48:49], v[16:17], v[36:37] op_sel_hi:[1,0]
	v_lshl_add_u64 v[44:45], v[38:39], 0, v[102:103]
	s_waitcnt vmcnt(0)
	v_pk_fma_f32 v[20:21], v[20:21], v[48:49], v[28:29]
	v_pk_fma_f32 v[22:23], v[22:23], v[46:47], v[30:31]
	global_store_dwordx4 v[44:45], v[20:23], off
	global_load_dwordx4 v[20:23], v[78:79], off
	s_nop 0
	global_load_dwordx4 v[28:31], v[80:81], off
	v_pk_mul_f32 v[46:47], v[26:27], v[36:37] op_sel_hi:[1,0]
	v_pk_mul_f32 v[48:49], v[24:25], v[36:37] op_sel_hi:[1,0]
	v_lshl_add_u64 v[44:45], v[38:39], 0, v[104:105]
	s_waitcnt vmcnt(0)
	v_pk_fma_f32 v[20:21], v[20:21], v[48:49], v[28:29]
	v_pk_fma_f32 v[22:23], v[22:23], v[46:47], v[30:31]
	global_store_dwordx4 v[44:45], v[20:23], off
	global_load_dwordx4 v[20:23], v[82:83], off
	s_nop 0
	global_load_dwordx4 v[28:31], v[84:85], off
	v_pk_mul_f32 v[46:47], v[34:35], v[36:37] op_sel_hi:[1,0]
	v_pk_mul_f32 v[48:49], v[32:33], v[36:37] op_sel_hi:[1,0]
	v_lshl_add_u64 v[44:45], v[38:39], 0, v[106:107]
	s_waitcnt vmcnt(0)
	v_pk_fma_f32 v[20:21], v[20:21], v[48:49], v[28:29]
	v_pk_fma_f32 v[22:23], v[22:23], v[46:47], v[30:31]
	global_store_dwordx4 v[44:45], v[20:23], off
	global_load_dwordx4 v[20:23], v[86:87], off
	s_nop 0
	global_load_dwordx4 v[28:31], v[88:89], off
	v_pk_mul_f32 v[44:45], v[42:43], v[36:37] op_sel_hi:[1,0]
	v_pk_mul_f32 v[36:37], v[40:41], v[36:37] op_sel_hi:[1,0]
	s_waitcnt vmcnt(0)
	v_pk_fma_f32 v[22:23], v[22:23], v[44:45], v[30:31]
	v_pk_fma_f32 v[20:21], v[20:21], v[36:37], v[28:29]
	v_lshl_add_u64 v[28:29], v[38:39], 0, v[108:109]
	global_store_dwordx4 v[28:29], v[20:23], off
	s_branch .LBB0_1494
